# stack on k33: POST cross-lane reductions via DPP/permlane swaps + DSA scoring 8-deep LDS fragment prefetch with merged waits + DSA gather saddr-form loads
# speedup vs baseline: 1.0126x; 1.0126x over previous
; DI float sum32(float v) { v += __shfl_xor(v, 16); return sum16(v); }
; DI f32x2 unpk(unsigned w) { f32x2 r = {bflo(w), bfhi(w)}; return r; }
; DI void post_unit(const Params& p, int l, int unit, LAS unsigned char* lds) {
;     ...
;     for (int hf = 0; hf < 2; ++hf) { const u16* rowl = proj + (tok0 + w * 8 + 2 * tp + hf) * NP;
; #pragma unroll
;       for (int s = 0; s < 16; ++s) raw2[hf][s] = *(const unsigned*)(rowl + segcol[s] + 2 * lane); }
; #pragma unroll
;     for (int hf = 0; hf < 2; ++hf) {
;     const int t = w * 8 + 2 * tp + hf; u16* row = proj + (tok0 + t) * NP;
; #pragma unroll
;     for (int s = 0; s < 16; ++s) {
;       f32x2 x = unpk(raw2[hf][s]); u16* pp = row + segcol[s] + 2 * lane;
;       if (s < 2) {
;         const float rs = rsqrtf(sum32(x[0] * x[0] + x[1] * x[1]) * (1.0f / 64.0f) + EPS);
;         x[0] *= rs * qna[2 * hl]; x[1] *= rs * qna[2 * hl + 1]; rope2<4>(x, hl, cs16 + t * 8);
.LBB0_150:
	v_lshl_add_u64 v[18:19], v[12:13], 0, v[0:1]
	v_add_co_u32_e32 v20, vcc, 0xa000000, v18
	s_mov_b32 s2, 0xa001000
	s_waitcnt lgkmcnt(0)
	v_addc_co_u32_e32 v21, vcc, 0, v19, vcc
	global_load_dword v49, v[20:21], off
	v_add_co_u32_e32 v22, vcc, s2, v18
	s_mov_b32 s2, 0xa003000
	s_nop 0
	v_addc_co_u32_e32 v23, vcc, 0, v19, vcc
	v_add_co_u32_e32 v42, vcc, s77, v18
	global_load_dword v59, v[20:21], off offset:512
	global_load_dword v70, v[20:21], off offset:768
	global_load_dword v69, v[20:21], off offset:1024
	global_load_dword v68, v[20:21], off offset:1280
	global_load_dword v67, v[20:21], off offset:1536
	global_load_dword v58, v[20:21], off offset:1792
	global_load_dword v71, v[20:21], off offset:256
	v_addc_co_u32_e32 v43, vcc, 0, v19, vcc
	global_load_dword v56, v[20:21], off offset:2432
	global_load_dword v66, v[20:21], off offset:2688
	global_load_dword v65, v[20:21], off offset:2944
	global_load_dword v64, v[20:21], off offset:3200
	global_load_dword v54, v[22:23], off offset:384
	global_load_dword v63, v[22:23], off offset:640
	global_load_dword v62, v[22:23], off offset:896
	global_load_dword v61, v[22:23], off offset:1152
	v_add_co_u32_e32 v20, vcc, s2, v18
	global_load_dword v60, v[42:43], off offset:512
	global_load_dword v57, v[42:43], off offset:768
	global_load_dword v55, v[42:43], off offset:1024
	global_load_dword v53, v[42:43], off offset:1280
	global_load_dword v52, v[42:43], off offset:1536
	global_load_dword v51, v[42:43], off offset:1792
	global_load_dword v50, v[42:43], off offset:2048
	global_load_dword v48, v[42:43], off offset:2304
	v_addc_co_u32_e32 v21, vcc, 0, v19, vcc
	global_load_dword v47, v[42:43], off offset:2944
	global_load_dword v46, v[42:43], off offset:3200
	global_load_dword v45, v[42:43], off offset:3456
	global_load_dword v44, v[42:43], off offset:3712
	s_nop 0
	global_load_dword v43, v[20:21], off offset:896
	global_load_dword v42, v[20:21], off offset:1152
	global_load_dword v41, v[20:21], off offset:1408
	global_load_dword v3, v[20:21], off offset:1664
	s_waitcnt vmcnt(31)
	v_and_b32_e32 v21, 0xffff0000, v49
	v_lshlrev_b32_e32 v20, 16, v49
	v_pk_mul_f32 v[22:23], v[20:21], v[20:21]
	s_nop 0
	v_add_f32_e32 v22, v22, v23
	v_mov_b32_e32 v23, v22
	s_nop 1
	v_permlane16_swap_b32_e32 v22, v23
	v_add_f32_e32 v22, v22, v23
	s_nop 1
	v_add_f32_dpp v22, v22, v22 row_ror:8 row_mask:0xf bank_mask:0xf
	s_nop 1
	v_add_f32_dpp v22, v22, v22 row_ror:4 row_mask:0xf bank_mask:0xf
	s_nop 1
	v_add_f32_dpp v22, v22, v22 quad_perm:[2,3,0,1] row_mask:0xf bank_mask:0xf
	s_nop 1
	v_add_f32_dpp v22, v22, v22 quad_perm:[1,0,3,2] row_mask:0xf bank_mask:0xf
	v_fmamk_f32 v22, v22, 0x3c800000, v170
	v_mul_f32_e32 v23, 0x4b800000, v22
	v_cmp_gt_f32_e32 vcc, s33, v22
	s_nop 1
	v_cndmask_b32_e32 v22, v22, v23, vcc
	v_rsq_f32_e32 v22, v22
	s_nop 0
	v_mul_f32_e32 v23, 0x45800000, v22
	v_cndmask_b32_e32 v22, v22, v23, vcc
	v_pk_mul_f32 v[22:23], v[4:5], v[22:23] op_sel_hi:[1,0]
	s_nop 0
	v_pk_mul_f32 v[22:23], v[22:23], v[20:21]
	ds_bpermute_b32 v20, v28, v22
	ds_bpermute_b32 v21, v28, v23
	s_and_saveexec_b64 s[2:3], s[12:13]
	s_xor_b64 s[18:19], exec, s[2:3]
	s_cbranch_execz .LBB0_154
	s_and_saveexec_b64 s[30:31], s[14:15]
	s_cbranch_execz .LBB0_153
	v_add_u32_e32 v49, 0, v35
	ds_read_b128 v[72:75], v49
	s_waitcnt lgkmcnt(0)
	v_pk_mul_f32 v[76:77], v[22:23], v[72:73]
	v_mul_f32_e32 v22, v73, v20
	v_mov_b32_e32 v20, v23
	v_pk_mul_f32 v[20:21], v[20:21], v[74:75]
	s_nop 0
	v_mov_b32_e32 v77, v20
	v_mov_b32_e32 v23, v21
	v_pk_add_f32 v[22:23], v[76:77], v[22:23]

; DI unsigned pk2(float lo, float hi) { f32x2 x = {lo, hi}; return __builtin_bit_cast(unsigned, __builtin_convertvector(x, bf16x2_t)); }
; DI float sum32(float v) { v += __shfl_xor(v, 16); return sum16(v); }
; DI f32x2 unpk(unsigned w) { f32x2 r = {bflo(w), bfhi(w)}; return r; }
; DI void post_unit(const Params& p, int l, int unit, LAS unsigned char* lds) {
;     ...
;       f32x2 x = unpk(raw2[hf][s]); u16* pp = row + segcol[s] + 2 * lane;
;       if (s < 2) {
;         const float rs = rsqrtf(sum32(x[0] * x[0] + x[1] * x[1]) * (1.0f / 64.0f) + EPS);
;         x[0] *= rs * qna[2 * hl]; x[1] *= rs * qna[2 * hl + 1]; rope2<4>(x, hl, cs16 + t * 8);
;         x *= LOG2E * 0.125f; *(unsigned*)pp = pk2(x[0], x[1]);
.LBB0_156:
	s_or_b64 exec, exec, s[18:19]
	s_mov_b64 s[2:3], 0xa000000
	s_waitcnt lgkmcnt(0)
	v_lshl_add_u64 v[20:21], v[18:19], 0, s[2:3]
	s_mov_b32 s2, 0x3e38aa3b
	v_pk_mul_f32 v[22:23], v[22:23], s[2:3] op_sel_hi:[1,0]
	s_nop 0
	v_cvt_pk_bf16_f32 v22, v22, v23
	global_store_dword v[20:21], v22, off
	s_waitcnt vmcnt(25)
	v_and_b32_e32 v21, 0xffff0000, v71
	v_lshlrev_b32_e32 v20, 16, v71
	v_pk_mul_f32 v[22:23], v[20:21], v[20:21]
	s_nop 0
	v_add_f32_e32 v22, v22, v23
	v_mov_b32_e32 v23, v22
	s_nop 1
	v_permlane16_swap_b32_e32 v22, v23
	v_add_f32_e32 v22, v22, v23
	s_nop 1
	v_add_f32_dpp v22, v22, v22 row_ror:8 row_mask:0xf bank_mask:0xf
	s_nop 1
	v_add_f32_dpp v22, v22, v22 row_ror:4 row_mask:0xf bank_mask:0xf
	s_nop 1
	v_add_f32_dpp v22, v22, v22 quad_perm:[2,3,0,1] row_mask:0xf bank_mask:0xf
	s_nop 1
	v_add_f32_dpp v22, v22, v22 quad_perm:[1,0,3,2] row_mask:0xf bank_mask:0xf
	v_fmamk_f32 v22, v22, 0x3c800000, v170
	v_cmp_gt_f32_e32 vcc, s33, v22
	v_mul_f32_e32 v23, 0x4b800000, v22
	s_nop 0
	v_cndmask_b32_e32 v22, v22, v23, vcc
	v_rsq_f32_e32 v22, v22
	s_nop 0
	v_mul_f32_e32 v23, 0x45800000, v22
	v_cndmask_b32_e32 v22, v22, v23, vcc
	v_pk_mul_f32 v[22:23], v[4:5], v[22:23] op_sel_hi:[1,0]
	s_nop 0
	v_pk_mul_f32 v[22:23], v[22:23], v[20:21]
	ds_bpermute_b32 v20, v28, v22
	ds_bpermute_b32 v21, v28, v23
	s_and_saveexec_b64 s[2:3], s[12:13]
	s_xor_b64 s[18:19], exec, s[2:3]
	s_cbranch_execz .LBB0_160
	s_and_saveexec_b64 s[30:31], s[14:15]
	s_cbranch_execz .LBB0_159
	ds_read_b128 v[72:75], v49
	s_waitcnt lgkmcnt(0)
	v_pk_mul_f32 v[76:77], v[22:23], v[72:73]
	v_mul_f32_e32 v22, v73, v20
	v_mov_b32_e32 v20, v23
	v_pk_mul_f32 v[20:21], v[20:21], v[74:75]
	s_nop 0
	v_mov_b32_e32 v77, v20
	v_mov_b32_e32 v23, v21
	v_pk_add_f32 v[22:23], v[76:77], v[22:23]

; #define LAS __attribute__((address_space(3)))
; DI unsigned pk2(float lo, float hi) { f32x2 x = {lo, hi}; return __builtin_bit_cast(unsigned, __builtin_convertvector(x, bf16x2_t)); }
; DI float sum64(float v) { v += __shfl_xor(v, 32); return sum32(v); }
; DI void post_unit(const Params& p, int l, int unit, LAS unsigned char* lds) {
;     ...
;         x *= LOG2E * 0.125f; *(unsigned*)pp = pk2(x[0], x[1]);
;       } else if (s == 2) {
;         const float rs = rsqrtf(sum64(x[0] * x[0] + x[1] * x[1]) * (1.0f / 128.0f) + EPS);
;         *(LAS unsigned*)(At + t * 272 + lane * 4) = pk2(x[0] * rs, x[1] * rs);
;       } else if (s < 7) {
;         rope2<4>(x, hl, cs16 + t * 8); *(unsigned*)pp = pk2(x[0], x[1]);
.LBB0_162:
	s_or_b64 exec, exec, s[18:19]
	s_mov_b64 s[2:3], 0xa000100
	s_waitcnt lgkmcnt(0)
	v_lshl_add_u64 v[20:21], v[18:19], 0, s[2:3]
	s_mov_b32 s2, 0x3e38aa3b
	v_pk_mul_f32 v[22:23], v[22:23], s[2:3] op_sel_hi:[1,0]
	s_nop 0
	v_cvt_pk_bf16_f32 v22, v22, v23
	global_store_dword v[20:21], v22, off
	v_lshlrev_b32_e32 v20, 16, v59
	v_and_b32_e32 v21, 0xffff0000, v59
	v_pk_mul_f32 v[22:23], v[20:21], v[20:21]
	v_add_u32_e32 v59, 0, v33
	v_add_f32_e32 v22, v22, v23
	v_mov_b32_e32 v23, v22
	s_nop 1
	v_permlane32_swap_b32_e32 v22, v23
	v_add_f32_e32 v22, v22, v23
	v_mov_b32_e32 v23, v22
	s_nop 1
	v_permlane16_swap_b32_e32 v22, v23
	v_add_f32_e32 v22, v22, v23
	s_nop 1
	v_add_f32_dpp v22, v22, v22 row_ror:8 row_mask:0xf bank_mask:0xf
	s_nop 1
	v_add_f32_dpp v22, v22, v22 row_ror:4 row_mask:0xf bank_mask:0xf
	s_nop 1
	v_add_f32_dpp v22, v22, v22 quad_perm:[2,3,0,1] row_mask:0xf bank_mask:0xf
	s_nop 1
	v_add_f32_dpp v22, v22, v22 quad_perm:[1,0,3,2] row_mask:0xf bank_mask:0xf
	v_fmamk_f32 v22, v22, 0x3c000000, v170
	v_cmp_gt_f32_e32 vcc, s33, v22
	v_mul_f32_e32 v23, 0x4b800000, v22
	s_nop 0
	v_cndmask_b32_e32 v22, v22, v23, vcc
	v_rsq_f32_e32 v22, v22
	s_nop 0
	v_mul_f32_e32 v23, 0x45800000, v22
	v_cndmask_b32_e32 v22, v22, v23, vcc
	v_pk_mul_f32 v[20:21], v[22:23], v[20:21] op_sel_hi:[0,1]
	v_cvt_pk_bf16_f32 v20, v20, v21
	ds_write_b32 v59, v20
	v_lshlrev_b32_e32 v20, 16, v70
	v_and_b32_e32 v21, 0xffff0000, v70
	ds_bpermute_b32 v70, v28, v20
	ds_bpermute_b32 v23, v28, v21
	s_and_saveexec_b64 s[2:3], s[12:13]
	s_xor_b64 s[18:19], exec, s[2:3]
	s_cbranch_execz .LBB0_166
	s_and_saveexec_b64 s[30:31], s[14:15]
	s_cbranch_execz .LBB0_165
	ds_read_b128 v[72:75], v49
	v_mov_b32_e32 v22, v21
	s_waitcnt lgkmcnt(0)
	v_pk_mul_f32 v[22:23], v[74:75], v[22:23]
	v_mul_f32_e32 v20, v72, v20
	v_mul_f32_e32 v70, v73, v70
	v_mov_b32_e32 v21, v22
	v_mov_b32_e32 v71, v23
	v_pk_add_f32 v[20:21], v[20:21], v[70:71]

; DI unsigned pk2(float lo, float hi) { f32x2 x = {lo, hi}; return __builtin_bit_cast(unsigned, __builtin_convertvector(x, bf16x2_t)); }
; DI float sum32(float v) { v += __shfl_xor(v, 16); return sum16(v); }
; DI void post_unit(const Params& p, int l, int unit, LAS unsigned char* lds) {
;     ...
;       } else if (s < 7) {
;         rope2<4>(x, hl, cs16 + t * 8); *(unsigned*)pp = pk2(x[0], x[1]);
;       } else if (s == 7) {
;         const float rs = rsqrtf(sum32(x[0] * x[0] + x[1] * x[1]) * (1.0f / 64.0f) + EPS);
;         x *= rs; rope2<4>(x, hl, cs16 + t * 8); if (lane < 32) *(unsigned*)((u16*)(p.ws + WS_KIC) + (tok0 + t) * 64 + 2 * lane) = pk2(x[0], x[1]);
.LBB0_186:
	s_or_b64 exec, exec, s[18:19]
	s_mov_b64 s[2:3], 0xa000600
	s_waitcnt lgkmcnt(0)
	v_lshl_add_u64 v[22:23], v[18:19], 0, s[2:3]
	v_cvt_pk_bf16_f32 v20, v20, v21
	global_store_dword v[22:23], v20, off
	v_lshlrev_b32_e32 v20, 16, v58
	v_and_b32_e32 v21, 0xffff0000, v58
	v_pk_mul_f32 v[22:23], v[20:21], v[20:21]
	s_nop 0
	v_add_f32_e32 v22, v22, v23
	v_mov_b32_e32 v23, v22
	s_nop 1
	v_permlane16_swap_b32_e32 v22, v23
	v_add_f32_e32 v22, v22, v23
	s_nop 1
	v_add_f32_dpp v22, v22, v22 row_ror:8 row_mask:0xf bank_mask:0xf
	s_nop 1
	v_add_f32_dpp v22, v22, v22 row_ror:4 row_mask:0xf bank_mask:0xf
	s_nop 1
	v_add_f32_dpp v22, v22, v22 quad_perm:[2,3,0,1] row_mask:0xf bank_mask:0xf
	s_nop 1
	v_add_f32_dpp v22, v22, v22 quad_perm:[1,0,3,2] row_mask:0xf bank_mask:0xf
	v_fmamk_f32 v22, v22, 0x3c800000, v170
	v_cmp_gt_f32_e32 vcc, s33, v22
	v_mul_f32_e32 v23, 0x4b800000, v22
	s_nop 0
	v_cndmask_b32_e32 v22, v22, v23, vcc
	v_rsq_f32_e32 v22, v22
	s_nop 0
	v_mul_f32_e32 v23, 0x45800000, v22
	v_cndmask_b32_e32 v22, v22, v23, vcc
	v_pk_mul_f32 v[20:21], v[22:23], v[20:21] op_sel_hi:[0,1]
	ds_bpermute_b32 v22, v28, v20
	ds_bpermute_b32 v23, v28, v21
	s_and_saveexec_b64 s[2:3], s[12:13]
	s_xor_b64 s[18:19], exec, s[2:3]
	s_cbranch_execz .LBB0_314
	s_and_saveexec_b64 s[30:31], s[14:15]
	s_cbranch_execz .LBB0_189
	ds_read_b128 v[68:71], v49
	s_waitcnt lgkmcnt(0)
	v_pk_mul_f32 v[72:73], v[20:21], v[68:69]
	v_mul_f32_e32 v20, v69, v22
	v_mov_b32_e32 v22, v21
	v_pk_mul_f32 v[22:23], v[70:71], v[22:23]
	s_nop 0
	v_mov_b32_e32 v73, v22
	v_mov_b32_e32 v21, v23
	v_pk_add_f32 v[20:21], v[72:73], v[20:21]

; DI unsigned pk2(float lo, float hi) { f32x2 x = {lo, hi}; return __builtin_bit_cast(unsigned, __builtin_convertvector(x, bf16x2_t)); }
; DI float sum16(float v) { v += __shfl_xor(v, 8); v += __shfl_xor(v, 4); v += __shfl_xor(v, 2); v += __shfl_xor(v, 1); return v; }
; DI void post_unit(const Params& p, int l, int unit, LAS unsigned char* lds) {
;     ...
;       } else if (s < 12) {
;         rope2<16>(x, hl, cs64 + t * 32);
;         const int hd = ((s & 1) ? 2 : 0) + hsel;
;         const float lg = log1pf(-exp2f(-5.0f - (float)hd));
;         const float f = (s < 10) ? expf(lg * (float)(t + 1)) : expf(lg * (float)(63 - t)) * 0.125f;
;         x *= f; *(unsigned*)pp = pk2(x[0], x[1]);
;       } else {
;         const float* gn = (s < 14) ? qnc : knc;
;         const float rs = rsqrtf(sum16(x[0] * x[0] + x[1] * x[1]) * (1.0f / 32.0f) + EPS);
;         x[0] *= rs * gn[2 * hl16]; x[1] *= rs * gn[2 * hl16 + 1]; rope2<2>(x, hl16, cs8 + t * 4);
;         if (s < 14) x *= LOG2E * 0.17677669529663687f;
;         *(unsigned*)pp = pk2(x[0], x[1]);
.LBB0_208:
	s_or_b64 exec, exec, s[18:19]
	s_waitcnt lgkmcnt(1)
	v_mul_f32_e32 v64, v32, v65
	v_mul_f32_e32 v65, 0x3fb8aa3b, v64
	v_fma_f32 v66, v64, s64, -v65
	v_rndne_f32_e32 v67, v65
	v_fmac_f32_e32 v66, 0x32a5705f, v64
	v_sub_f32_e32 v65, v65, v67
	v_add_f32_e32 v65, v65, v66
	v_exp_f32_e32 v65, v65
	v_cvt_i32_f32_e32 v66, v67
	v_cmp_ngt_f32_e32 vcc, s65, v64
	s_mov_b64 s[2:3], 0xa000c80
	s_waitcnt lgkmcnt(0)
	v_lshl_add_u64 v[20:21], v[18:19], 0, s[2:3]
	v_ldexp_f32 v65, v65, v66
	v_cndmask_b32_e32 v65, 0, v65, vcc
	v_cmp_nlt_f32_e32 vcc, s89, v64
	s_nop 1
	v_cndmask_b32_e32 v64, v177, v65, vcc
	v_mul_f32_e32 v64, 0x3e000000, v64
	v_pk_mul_f32 v[22:23], v[64:65], v[22:23] op_sel_hi:[0,1]
	v_cvt_pk_bf16_f32 v22, v22, v23
	global_store_dword v[20:21], v22, off
	s_waitcnt vmcnt(29)
	v_lshlrev_b32_e32 v20, 16, v54
	v_and_b32_e32 v21, 0xffff0000, v54
	v_pk_mul_f32 v[22:23], v[20:21], v[20:21]
	s_nop 0
	v_add_f32_e32 v22, v22, v23
	s_nop 1
	v_add_f32_dpp v22, v22, v22 row_ror:8 row_mask:0xf bank_mask:0xf
	s_nop 1
	v_add_f32_dpp v22, v22, v22 row_ror:4 row_mask:0xf bank_mask:0xf
	s_nop 1
	v_add_f32_dpp v22, v22, v22 quad_perm:[2,3,0,1] row_mask:0xf bank_mask:0xf
	s_nop 1
	v_add_f32_dpp v22, v22, v22 quad_perm:[1,0,3,2] row_mask:0xf bank_mask:0xf
	v_fmamk_f32 v22, v22, 0x3d000000, v170
	v_cmp_gt_f32_e32 vcc, s33, v22
	v_mul_f32_e32 v23, 0x4b800000, v22
	s_nop 0
	v_cndmask_b32_e32 v22, v22, v23, vcc
	v_rsq_f32_e32 v22, v22
	s_nop 0
	v_mul_f32_e32 v23, 0x45800000, v22
	v_cndmask_b32_e32 v22, v22, v23, vcc
	v_pk_mul_f32 v[22:23], v[6:7], v[22:23] op_sel_hi:[1,0]
	s_nop 0
	v_pk_mul_f32 v[22:23], v[22:23], v[20:21]
	ds_bpermute_b32 v20, v29, v22
	ds_bpermute_b32 v21, v29, v23
	s_and_saveexec_b64 s[2:3], s[6:7]
	s_xor_b64 s[18:19], exec, s[2:3]
	s_cbranch_execz .LBB0_212
	s_and_saveexec_b64 s[30:31], s[8:9]
	s_cbranch_execz .LBB0_211
	v_add_u32_e32 v54, 0, v40
	ds_read_b128 v[64:67], v54
	s_waitcnt lgkmcnt(0)
	v_pk_mul_f32 v[68:69], v[22:23], v[64:65]
	v_mul_f32_e32 v22, v65, v20
	v_mov_b32_e32 v20, v23
	v_pk_mul_f32 v[20:21], v[20:21], v[66:67]
	s_nop 0
	v_mov_b32_e32 v69, v20
	v_mov_b32_e32 v23, v21
	v_pk_add_f32 v[22:23], v[68:69], v[22:23]

; DI unsigned pk2(float lo, float hi) { f32x2 x = {lo, hi}; return __builtin_bit_cast(unsigned, __builtin_convertvector(x, bf16x2_t)); }
; DI float sum16(float v) { v += __shfl_xor(v, 8); v += __shfl_xor(v, 4); v += __shfl_xor(v, 2); v += __shfl_xor(v, 1); return v; }
; DI void post_unit(const Params& p, int l, int unit, LAS unsigned char* lds) {
;     ...
;       } else {
;         const float* gn = (s < 14) ? qnc : knc;
;         const float rs = rsqrtf(sum16(x[0] * x[0] + x[1] * x[1]) * (1.0f / 32.0f) + EPS);
;         x[0] *= rs * gn[2 * hl16]; x[1] *= rs * gn[2 * hl16 + 1]; rope2<2>(x, hl16, cs8 + t * 4);
;         if (s < 14) x *= LOG2E * 0.17677669529663687f;
;         *(unsigned*)pp = pk2(x[0], x[1]);
.LBB0_214:
	s_or_b64 exec, exec, s[18:19]
	s_mov_b64 s[2:3], 0xa001180
	s_waitcnt lgkmcnt(0)
	v_lshl_add_u64 v[20:21], v[18:19], 0, s[2:3]
	s_mov_b32 s2, 0x3e8293ee
	v_pk_mul_f32 v[22:23], v[22:23], s[2:3] op_sel_hi:[1,0]
	s_nop 0
	v_cvt_pk_bf16_f32 v22, v22, v23
	global_store_dword v[20:21], v22, off
	s_waitcnt vmcnt(29)
	v_lshlrev_b32_e32 v20, 16, v63
	v_and_b32_e32 v21, 0xffff0000, v63
	v_pk_mul_f32 v[22:23], v[20:21], v[20:21]
	s_nop 0
	v_add_f32_e32 v22, v22, v23
	s_nop 1
	v_add_f32_dpp v22, v22, v22 row_ror:8 row_mask:0xf bank_mask:0xf
	s_nop 1
	v_add_f32_dpp v22, v22, v22 row_ror:4 row_mask:0xf bank_mask:0xf
	s_nop 1
	v_add_f32_dpp v22, v22, v22 quad_perm:[2,3,0,1] row_mask:0xf bank_mask:0xf
	s_nop 1
	v_add_f32_dpp v22, v22, v22 quad_perm:[1,0,3,2] row_mask:0xf bank_mask:0xf
	v_fmamk_f32 v22, v22, 0x3d000000, v170
	v_cmp_gt_f32_e32 vcc, s33, v22
	v_mul_f32_e32 v23, 0x4b800000, v22
	s_nop 0
	v_cndmask_b32_e32 v22, v22, v23, vcc
	v_rsq_f32_e32 v22, v22
	s_nop 0
	v_mul_f32_e32 v23, 0x45800000, v22
	v_cndmask_b32_e32 v22, v22, v23, vcc
	v_pk_mul_f32 v[22:23], v[6:7], v[22:23] op_sel_hi:[1,0]
	s_nop 0
	v_pk_mul_f32 v[22:23], v[22:23], v[20:21]
	ds_bpermute_b32 v20, v29, v22
	ds_bpermute_b32 v21, v29, v23
	s_and_saveexec_b64 s[2:3], s[6:7]
	s_xor_b64 s[18:19], exec, s[2:3]
	s_cbranch_execz .LBB0_218
	s_and_saveexec_b64 s[30:31], s[8:9]
	s_cbranch_execz .LBB0_217
	ds_read_b128 v[64:67], v54
	s_waitcnt lgkmcnt(0)
	v_pk_mul_f32 v[68:69], v[22:23], v[64:65]
	v_mul_f32_e32 v22, v65, v20
	v_mov_b32_e32 v20, v23
	v_pk_mul_f32 v[20:21], v[20:21], v[66:67]
	s_nop 0
	v_mov_b32_e32 v69, v20
	v_mov_b32_e32 v23, v21
	v_pk_add_f32 v[22:23], v[68:69], v[22:23]

; DI unsigned pk2(float lo, float hi) { f32x2 x = {lo, hi}; return __builtin_bit_cast(unsigned, __builtin_convertvector(x, bf16x2_t)); }
; DI float sum16(float v) { v += __shfl_xor(v, 8); v += __shfl_xor(v, 4); v += __shfl_xor(v, 2); v += __shfl_xor(v, 1); return v; }
; DI void post_unit(const Params& p, int l, int unit, LAS unsigned char* lds) {
;     ...
;       } else {
;         const float* gn = (s < 14) ? qnc : knc;
;         const float rs = rsqrtf(sum16(x[0] * x[0] + x[1] * x[1]) * (1.0f / 32.0f) + EPS);
;         x[0] *= rs * gn[2 * hl16]; x[1] *= rs * gn[2 * hl16 + 1]; rope2<2>(x, hl16, cs8 + t * 4);
;         if (s < 14) x *= LOG2E * 0.17677669529663687f;
;         *(unsigned*)pp = pk2(x[0], x[1]);
.LBB0_220:
	s_or_b64 exec, exec, s[18:19]
	s_mov_b64 s[2:3], 0xa001280
	s_waitcnt lgkmcnt(0)
	v_lshl_add_u64 v[20:21], v[18:19], 0, s[2:3]
	s_mov_b32 s2, 0x3e8293ee
	v_pk_mul_f32 v[22:23], v[22:23], s[2:3] op_sel_hi:[1,0]
	s_nop 0
	v_cvt_pk_bf16_f32 v22, v22, v23
	global_store_dword v[20:21], v22, off
	s_waitcnt vmcnt(29)
	v_lshlrev_b32_e32 v20, 16, v62
	v_and_b32_e32 v21, 0xffff0000, v62
	v_pk_mul_f32 v[22:23], v[20:21], v[20:21]
	s_nop 0
	v_add_f32_e32 v22, v22, v23
	s_nop 1
	v_add_f32_dpp v22, v22, v22 row_ror:8 row_mask:0xf bank_mask:0xf
	s_nop 1
	v_add_f32_dpp v22, v22, v22 row_ror:4 row_mask:0xf bank_mask:0xf
	s_nop 1
	v_add_f32_dpp v22, v22, v22 quad_perm:[2,3,0,1] row_mask:0xf bank_mask:0xf
	s_nop 1
	v_add_f32_dpp v22, v22, v22 quad_perm:[1,0,3,2] row_mask:0xf bank_mask:0xf
	v_fmamk_f32 v22, v22, 0x3d000000, v170
	v_cmp_gt_f32_e32 vcc, s33, v22
	v_mul_f32_e32 v23, 0x4b800000, v22
	s_nop 0
	v_cndmask_b32_e32 v22, v22, v23, vcc
	v_rsq_f32_e32 v22, v22
	s_nop 0
	v_mul_f32_e32 v23, 0x45800000, v22
	v_cndmask_b32_e32 v22, v22, v23, vcc
	v_pk_mul_f32 v[22:23], v[8:9], v[22:23] op_sel_hi:[1,0]
	s_nop 0
	v_pk_mul_f32 v[22:23], v[22:23], v[20:21]
	ds_bpermute_b32 v20, v29, v22
	ds_bpermute_b32 v21, v29, v23
	s_and_saveexec_b64 s[2:3], s[6:7]
	s_xor_b64 s[18:19], exec, s[2:3]
	s_cbranch_execz .LBB0_224
	s_and_saveexec_b64 s[30:31], s[8:9]
	s_cbranch_execz .LBB0_223
	ds_read_b128 v[62:65], v54
	s_waitcnt lgkmcnt(0)
	v_pk_mul_f32 v[66:67], v[22:23], v[62:63]
	v_mul_f32_e32 v22, v63, v20
	v_mov_b32_e32 v20, v23
	v_pk_mul_f32 v[20:21], v[20:21], v[64:65]
	s_nop 0
	v_mov_b32_e32 v67, v20
	v_mov_b32_e32 v23, v21
	v_pk_add_f32 v[22:23], v[66:67], v[22:23]

; DI unsigned pk2(float lo, float hi) { f32x2 x = {lo, hi}; return __builtin_bit_cast(unsigned, __builtin_convertvector(x, bf16x2_t)); }
; DI float sum16(float v) { v += __shfl_xor(v, 8); v += __shfl_xor(v, 4); v += __shfl_xor(v, 2); v += __shfl_xor(v, 1); return v; }
; DI void post_unit(const Params& p, int l, int unit, LAS unsigned char* lds) {
;     ...
;       } else {
;         const float* gn = (s < 14) ? qnc : knc;
;         const float rs = rsqrtf(sum16(x[0] * x[0] + x[1] * x[1]) * (1.0f / 32.0f) + EPS);
;         x[0] *= rs * gn[2 * hl16]; x[1] *= rs * gn[2 * hl16 + 1]; rope2<2>(x, hl16, cs8 + t * 4);
;         if (s < 14) x *= LOG2E * 0.17677669529663687f;
;         *(unsigned*)pp = pk2(x[0], x[1]);
.LBB0_226:
	s_or_b64 exec, exec, s[18:19]
	s_mov_b64 s[2:3], 0xa001380
	s_waitcnt lgkmcnt(0)
	v_lshl_add_u64 v[20:21], v[18:19], 0, s[2:3]
	v_cvt_pk_bf16_f32 v22, v22, v23
	global_store_dword v[20:21], v22, off
	s_waitcnt vmcnt(29)
	v_lshlrev_b32_e32 v20, 16, v61
	v_and_b32_e32 v21, 0xffff0000, v61
	v_pk_mul_f32 v[22:23], v[20:21], v[20:21]
	s_nop 0
	v_add_f32_e32 v22, v22, v23
	s_nop 1
	v_add_f32_dpp v22, v22, v22 row_ror:8 row_mask:0xf bank_mask:0xf
	s_nop 1
	v_add_f32_dpp v22, v22, v22 row_ror:4 row_mask:0xf bank_mask:0xf
	s_nop 1
	v_add_f32_dpp v22, v22, v22 quad_perm:[2,3,0,1] row_mask:0xf bank_mask:0xf
	s_nop 1
	v_add_f32_dpp v22, v22, v22 quad_perm:[1,0,3,2] row_mask:0xf bank_mask:0xf
	v_fmamk_f32 v22, v22, 0x3d000000, v170
	v_cmp_gt_f32_e32 vcc, s33, v22
	v_mul_f32_e32 v23, 0x4b800000, v22
	s_nop 0
	v_cndmask_b32_e32 v22, v22, v23, vcc
	v_rsq_f32_e32 v22, v22
	s_nop 0
	v_mul_f32_e32 v23, 0x45800000, v22
	v_cndmask_b32_e32 v22, v22, v23, vcc
	v_pk_mul_f32 v[22:23], v[8:9], v[22:23] op_sel_hi:[1,0]
	s_nop 0
	v_pk_mul_f32 v[22:23], v[22:23], v[20:21]
	ds_bpermute_b32 v20, v29, v22
	ds_bpermute_b32 v21, v29, v23
	s_and_saveexec_b64 s[2:3], s[6:7]
	s_xor_b64 s[18:19], exec, s[2:3]
	s_cbranch_execz .LBB0_230
	s_and_saveexec_b64 s[30:31], s[8:9]
	s_cbranch_execz .LBB0_229
	ds_read_b128 v[62:65], v54
	s_waitcnt lgkmcnt(0)
	v_pk_mul_f32 v[66:67], v[22:23], v[62:63]
	v_mul_f32_e32 v22, v63, v20
	v_mov_b32_e32 v20, v23
	v_pk_mul_f32 v[20:21], v[20:21], v[64:65]
	s_nop 0
	v_mov_b32_e32 v67, v20
	v_mov_b32_e32 v23, v21
	v_pk_add_f32 v[22:23], v[66:67], v[22:23]

; DI unsigned pk2(float lo, float hi) { f32x2 x = {lo, hi}; return __builtin_bit_cast(unsigned, __builtin_convertvector(x, bf16x2_t)); }
; DI float sum16(float v) { v += __shfl_xor(v, 8); v += __shfl_xor(v, 4); v += __shfl_xor(v, 2); v += __shfl_xor(v, 1); return v; }
; DI float sum32(float v) { v += __shfl_xor(v, 16); return sum16(v); }
; DI f32x2 unpk(unsigned w) { f32x2 r = {bflo(w), bfhi(w)}; return r; }
; DI void post_unit(const Params& p, int l, int unit, LAS unsigned char* lds) {
;     ...
;     for (int hf = 0; hf < 2; ++hf) {
;     const int t = w * 8 + 2 * tp + hf; u16* row = proj + (tok0 + t) * NP;
; #pragma unroll
;     for (int s = 0; s < 16; ++s) {
;       f32x2 x = unpk(raw2[hf][s]); u16* pp = row + segcol[s] + 2 * lane;
;       if (s < 2) {
;         const float rs = rsqrtf(sum32(x[0] * x[0] + x[1] * x[1]) * (1.0f / 64.0f) + EPS);
;         x[0] *= rs * qna[2 * hl]; x[1] *= rs * qna[2 * hl + 1]; rope2<4>(x, hl, cs16 + t * 8);
;     ...
;       } else {
;         const float* gn = (s < 14) ? qnc : knc;
;         const float rs = rsqrtf(sum16(x[0] * x[0] + x[1] * x[1]) * (1.0f / 32.0f) + EPS);
;         x[0] *= rs * gn[2 * hl16]; x[1] *= rs * gn[2 * hl16 + 1]; rope2<2>(x, hl16, cs8 + t * 4);
;         if (s < 14) x *= LOG2E * 0.17677669529663687f;
;         *(unsigned*)pp = pk2(x[0], x[1]);
.LBB0_232:
	s_or_b64 exec, exec, s[18:19]
	s_mov_b64 s[2:3], 0xa001480
	v_lshl_add_u64 v[18:19], v[18:19], 0, s[2:3]
	s_waitcnt lgkmcnt(1)
	v_cvt_pk_bf16_f32 v20, v22, v23
	global_store_dword v[18:19], v20, off
	s_waitcnt vmcnt(29)
	v_and_b32_e32 v19, 0xffff0000, v60
	v_lshlrev_b32_e32 v18, 16, v60
	s_waitcnt lgkmcnt(0)
	v_pk_mul_f32 v[20:21], v[18:19], v[18:19]
	s_nop 0
	v_add_f32_e32 v20, v20, v21
	v_mov_b32_e32 v21, v20
	s_nop 1
	v_permlane16_swap_b32_e32 v20, v21
	v_add_f32_e32 v20, v20, v21
	s_nop 1
	v_add_f32_dpp v20, v20, v20 row_ror:8 row_mask:0xf bank_mask:0xf
	s_nop 1
	v_add_f32_dpp v20, v20, v20 row_ror:4 row_mask:0xf bank_mask:0xf
	s_nop 1
	v_add_f32_dpp v20, v20, v20 quad_perm:[2,3,0,1] row_mask:0xf bank_mask:0xf
	s_nop 1
	v_add_f32_dpp v20, v20, v20 quad_perm:[1,0,3,2] row_mask:0xf bank_mask:0xf
	v_fmamk_f32 v20, v20, 0x3c800000, v170
	v_cmp_gt_f32_e32 vcc, s33, v20
	v_mul_f32_e32 v21, 0x4b800000, v20
	s_nop 0
	v_cndmask_b32_e32 v20, v20, v21, vcc
	v_rsq_f32_e32 v20, v20
	s_nop 0
	v_mul_f32_e32 v21, 0x45800000, v20
	v_cndmask_b32_e32 v20, v20, v21, vcc
	v_pk_mul_f32 v[20:21], v[4:5], v[20:21] op_sel_hi:[1,0]
	s_nop 0
	v_pk_mul_f32 v[20:21], v[20:21], v[18:19]
	ds_bpermute_b32 v18, v28, v20
	ds_bpermute_b32 v19, v28, v21
	s_and_saveexec_b64 s[2:3], s[12:13]
	s_xor_b64 s[18:19], exec, s[2:3]
	s_cbranch_execz .LBB0_236
	s_and_saveexec_b64 s[30:31], s[14:15]
	s_cbranch_execz .LBB0_235
	ds_read_b128 v[60:63], v49 offset:64
	s_waitcnt lgkmcnt(0)
	v_pk_mul_f32 v[22:23], v[20:21], v[60:61]
	v_mul_f32_e32 v20, v61, v18
	v_mov_b32_e32 v18, v21
	v_pk_mul_f32 v[18:19], v[18:19], v[62:63]
	s_nop 0
	v_mov_b32_e32 v23, v18
	v_mov_b32_e32 v21, v19
	v_pk_add_f32 v[20:21], v[22:23], v[20:21]

; DI unsigned pk2(float lo, float hi) { f32x2 x = {lo, hi}; return __builtin_bit_cast(unsigned, __builtin_convertvector(x, bf16x2_t)); }
; DI float sum32(float v) { v += __shfl_xor(v, 16); return sum16(v); }
; DI f32x2 unpk(unsigned w) { f32x2 r = {bflo(w), bfhi(w)}; return r; }
; DI void post_unit(const Params& p, int l, int unit, LAS unsigned char* lds) {
;     ...
;       f32x2 x = unpk(raw2[hf][s]); u16* pp = row + segcol[s] + 2 * lane;
;       if (s < 2) {
;         const float rs = rsqrtf(sum32(x[0] * x[0] + x[1] * x[1]) * (1.0f / 64.0f) + EPS);
;         x[0] *= rs * qna[2 * hl]; x[1] *= rs * qna[2 * hl + 1]; rope2<4>(x, hl, cs16 + t * 8);
;         x *= LOG2E * 0.125f; *(unsigned*)pp = pk2(x[0], x[1]);
.LBB0_238:
	s_or_b64 exec, exec, s[18:19]
	s_mov_b32 s2, 0x3e38aa3b
	s_waitcnt lgkmcnt(0)
	v_lshl_add_u64 v[18:19], v[14:15], 0, v[0:1]
	v_pk_mul_f32 v[20:21], v[20:21], s[2:3] op_sel_hi:[1,0]
	s_nop 0
	v_cvt_pk_bf16_f32 v22, v20, v21
	v_add_co_u32_e32 v20, vcc, 0xa002000, v18
	s_nop 1
	v_addc_co_u32_e32 v21, vcc, 0, v19, vcc
	global_store_dword v[20:21], v22, off offset:512
	s_waitcnt vmcnt(29)
	v_and_b32_e32 v21, 0xffff0000, v57
	v_lshlrev_b32_e32 v20, 16, v57
	v_pk_mul_f32 v[22:23], v[20:21], v[20:21]
	s_nop 0
	v_add_f32_e32 v22, v22, v23
	v_mov_b32_e32 v23, v22
	s_nop 1
	v_permlane16_swap_b32_e32 v22, v23
	v_add_f32_e32 v22, v22, v23
	s_nop 1
	v_add_f32_dpp v22, v22, v22 row_ror:8 row_mask:0xf bank_mask:0xf
	s_nop 1
	v_add_f32_dpp v22, v22, v22 row_ror:4 row_mask:0xf bank_mask:0xf
	s_nop 1
	v_add_f32_dpp v22, v22, v22 quad_perm:[2,3,0,1] row_mask:0xf bank_mask:0xf
	s_nop 1
	v_add_f32_dpp v22, v22, v22 quad_perm:[1,0,3,2] row_mask:0xf bank_mask:0xf
	v_fmamk_f32 v22, v22, 0x3c800000, v170
	v_cmp_gt_f32_e32 vcc, s33, v22
	v_mul_f32_e32 v23, 0x4b800000, v22
	s_nop 0
	v_cndmask_b32_e32 v22, v22, v23, vcc
	v_rsq_f32_e32 v22, v22
	s_nop 0
	v_mul_f32_e32 v23, 0x45800000, v22
	v_cndmask_b32_e32 v22, v22, v23, vcc
	v_pk_mul_f32 v[22:23], v[4:5], v[22:23] op_sel_hi:[1,0]
	s_nop 0
	v_pk_mul_f32 v[22:23], v[22:23], v[20:21]
	ds_bpermute_b32 v20, v28, v22
	ds_bpermute_b32 v21, v28, v23
	s_and_saveexec_b64 s[2:3], s[12:13]
	s_xor_b64 s[18:19], exec, s[2:3]
	s_cbranch_execz .LBB0_242
	s_and_saveexec_b64 s[30:31], s[14:15]
	s_cbranch_execz .LBB0_241
	ds_read_b128 v[60:63], v49 offset:64
	s_waitcnt lgkmcnt(0)
	v_pk_mul_f32 v[64:65], v[22:23], v[60:61]
	v_mul_f32_e32 v22, v61, v20
	v_mov_b32_e32 v20, v23
	v_pk_mul_f32 v[20:21], v[20:21], v[62:63]
	s_nop 0
	v_mov_b32_e32 v65, v20
	v_mov_b32_e32 v23, v21
	v_pk_add_f32 v[22:23], v[64:65], v[22:23]

; #define LAS __attribute__((address_space(3)))
; DI unsigned pk2(float lo, float hi) { f32x2 x = {lo, hi}; return __builtin_bit_cast(unsigned, __builtin_convertvector(x, bf16x2_t)); }
; DI float sum32(float v) { v += __shfl_xor(v, 16); return sum16(v); }
; DI float sum64(float v) { v += __shfl_xor(v, 32); return sum32(v); }
; DI void post_unit(const Params& p, int l, int unit, LAS unsigned char* lds) {
;     ...
;       if (s < 2) {
;         const float rs = rsqrtf(sum32(x[0] * x[0] + x[1] * x[1]) * (1.0f / 64.0f) + EPS);
;         x[0] *= rs * qna[2 * hl]; x[1] *= rs * qna[2 * hl + 1]; rope2<4>(x, hl, cs16 + t * 8);
;         x *= LOG2E * 0.125f; *(unsigned*)pp = pk2(x[0], x[1]);
;       } else if (s == 2) {
;         const float rs = rsqrtf(sum64(x[0] * x[0] + x[1] * x[1]) * (1.0f / 128.0f) + EPS);
;         *(LAS unsigned*)(At + t * 272 + lane * 4) = pk2(x[0] * rs, x[1] * rs);
;       } else if (s < 7) {
;         rope2<4>(x, hl, cs16 + t * 8); *(unsigned*)pp = pk2(x[0], x[1]);
.LBB0_244:
	s_or_b64 exec, exec, s[18:19]
	s_mov_b32 s2, 0x3e38aa3b
	s_waitcnt lgkmcnt(0)
	v_pk_mul_f32 v[20:21], v[22:23], s[2:3] op_sel_hi:[1,0]
	s_nop 0
	v_cvt_pk_bf16_f32 v22, v20, v21
	v_add_co_u32_e32 v20, vcc, 0xa002000, v18
	s_nop 1
	v_addc_co_u32_e32 v21, vcc, 0, v19, vcc
	global_store_dword v[20:21], v22, off offset:768
	s_waitcnt vmcnt(29)
	v_lshlrev_b32_e32 v20, 16, v55
	v_and_b32_e32 v21, 0xffff0000, v55
	v_pk_mul_f32 v[22:23], v[20:21], v[20:21]
	s_nop 0
	v_add_f32_e32 v22, v22, v23
	v_mov_b32_e32 v23, v22
	s_nop 1
	v_permlane32_swap_b32_e32 v22, v23
	v_add_f32_e32 v22, v22, v23
	v_mov_b32_e32 v23, v22
	s_nop 1
	v_permlane16_swap_b32_e32 v22, v23
	v_add_f32_e32 v22, v22, v23
	s_nop 1
	v_add_f32_dpp v22, v22, v22 row_ror:8 row_mask:0xf bank_mask:0xf
	s_nop 1
	v_add_f32_dpp v22, v22, v22 row_ror:4 row_mask:0xf bank_mask:0xf
	s_nop 1
	v_add_f32_dpp v22, v22, v22 quad_perm:[2,3,0,1] row_mask:0xf bank_mask:0xf
	s_nop 1
	v_add_f32_dpp v22, v22, v22 quad_perm:[1,0,3,2] row_mask:0xf bank_mask:0xf
	v_fmamk_f32 v22, v22, 0x3c000000, v170
	v_cmp_gt_f32_e32 vcc, s33, v22
	v_mul_f32_e32 v23, 0x4b800000, v22
	s_nop 0
	v_cndmask_b32_e32 v22, v22, v23, vcc
	v_rsq_f32_e32 v22, v22
	s_nop 0
	v_mul_f32_e32 v23, 0x45800000, v22
	v_cndmask_b32_e32 v22, v22, v23, vcc
	v_pk_mul_f32 v[20:21], v[22:23], v[20:21] op_sel_hi:[0,1]
	v_cvt_pk_bf16_f32 v20, v20, v21
	ds_write_b32 v59, v20 offset:272
	s_waitcnt vmcnt(28)
	v_lshlrev_b32_e32 v20, 16, v53
	v_and_b32_e32 v21, 0xffff0000, v53
	ds_bpermute_b32 v53, v28, v20
	ds_bpermute_b32 v23, v28, v21
	s_and_saveexec_b64 s[2:3], s[12:13]
	s_xor_b64 s[18:19], exec, s[2:3]
	s_cbranch_execz .LBB0_248
	s_and_saveexec_b64 s[30:31], s[14:15]
	s_cbranch_execz .LBB0_247
	ds_read_b128 v[60:63], v49 offset:64
	v_mov_b32_e32 v22, v21
	s_waitcnt lgkmcnt(0)
	v_pk_mul_f32 v[22:23], v[62:63], v[22:23]
	v_mul_f32_e32 v20, v60, v20
	v_mul_f32_e32 v60, v61, v53
	v_mov_b32_e32 v21, v22
	v_mov_b32_e32 v61, v23
	v_pk_add_f32 v[20:21], v[20:21], v[60:61]

; DI unsigned pk2(float lo, float hi) { f32x2 x = {lo, hi}; return __builtin_bit_cast(unsigned, __builtin_convertvector(x, bf16x2_t)); }
; DI float sum32(float v) { v += __shfl_xor(v, 16); return sum16(v); }
; DI void post_unit(const Params& p, int l, int unit, LAS unsigned char* lds) {
;     ...
;       } else if (s < 7) {
;         rope2<4>(x, hl, cs16 + t * 8); *(unsigned*)pp = pk2(x[0], x[1]);
;       } else if (s == 7) {
;         const float rs = rsqrtf(sum32(x[0] * x[0] + x[1] * x[1]) * (1.0f / 64.0f) + EPS);
;         x *= rs; rope2<4>(x, hl, cs16 + t * 8); if (lane < 32) *(unsigned*)((u16*)(p.ws + WS_KIC) + (tok0 + t) * 64 + 2 * lane) = pk2(x[0], x[1]);
.LBB0_268:
	s_or_b64 exec, exec, s[18:19]
	v_cvt_pk_bf16_f32 v22, v20, v21
	v_add_co_u32_e32 v20, vcc, 0xa002000, v18
	s_nop 1
	v_addc_co_u32_e32 v21, vcc, 0, v19, vcc
	global_store_dword v[20:21], v22, off offset:2048
	s_waitcnt vmcnt(28)
	v_lshlrev_b32_e32 v20, 16, v48
	v_and_b32_e32 v21, 0xffff0000, v48
	s_waitcnt lgkmcnt(0)
	v_pk_mul_f32 v[22:23], v[20:21], v[20:21]
	s_nop 0
	v_add_f32_e32 v22, v22, v23
	v_mov_b32_e32 v23, v22
	s_nop 1
	v_permlane16_swap_b32_e32 v22, v23
	v_add_f32_e32 v22, v22, v23
	s_nop 1
	v_add_f32_dpp v22, v22, v22 row_ror:8 row_mask:0xf bank_mask:0xf
	s_nop 1
	v_add_f32_dpp v22, v22, v22 row_ror:4 row_mask:0xf bank_mask:0xf
	s_nop 1
	v_add_f32_dpp v22, v22, v22 quad_perm:[2,3,0,1] row_mask:0xf bank_mask:0xf
	s_nop 1
	v_add_f32_dpp v22, v22, v22 quad_perm:[1,0,3,2] row_mask:0xf bank_mask:0xf
	v_fmamk_f32 v22, v22, 0x3c800000, v170
	v_cmp_gt_f32_e32 vcc, s33, v22
	v_mul_f32_e32 v23, 0x4b800000, v22
	s_nop 0
	v_cndmask_b32_e32 v22, v22, v23, vcc
	v_rsq_f32_e32 v22, v22
	s_nop 0
	v_mul_f32_e32 v23, 0x45800000, v22
	v_cndmask_b32_e32 v22, v22, v23, vcc
	v_pk_mul_f32 v[20:21], v[22:23], v[20:21] op_sel_hi:[0,1]
	ds_bpermute_b32 v22, v28, v20
	ds_bpermute_b32 v23, v28, v21
	s_and_saveexec_b64 s[2:3], s[12:13]
	s_xor_b64 s[18:19], exec, s[2:3]
	s_cbranch_execz .LBB0_316
	s_and_saveexec_b64 s[30:31], s[14:15]
	s_cbranch_execz .LBB0_271
	ds_read_b128 v[48:51], v49 offset:64
	s_waitcnt lgkmcnt(0)
	v_pk_mul_f32 v[52:53], v[20:21], v[48:49]
	v_mul_f32_e32 v20, v49, v22
	v_mov_b32_e32 v22, v21
	v_pk_mul_f32 v[22:23], v[50:51], v[22:23]
	s_nop 0
	v_mov_b32_e32 v53, v22
	v_mov_b32_e32 v21, v23
	v_pk_add_f32 v[20:21], v[52:53], v[20:21]

; DI unsigned pk2(float lo, float hi) { f32x2 x = {lo, hi}; return __builtin_bit_cast(unsigned, __builtin_convertvector(x, bf16x2_t)); }
; DI float sum16(float v) { v += __shfl_xor(v, 8); v += __shfl_xor(v, 4); v += __shfl_xor(v, 2); v += __shfl_xor(v, 1); return v; }
; DI void post_unit(const Params& p, int l, int unit, LAS unsigned char* lds) {
;     ...
;       } else if (s < 12) {
;         rope2<16>(x, hl, cs64 + t * 32);
;         const int hd = ((s & 1) ? 2 : 0) + hsel;
;         const float lg = log1pf(-exp2f(-5.0f - (float)hd));
;         const float f = (s < 10) ? expf(lg * (float)(t + 1)) : expf(lg * (float)(63 - t)) * 0.125f;
;         x *= f; *(unsigned*)pp = pk2(x[0], x[1]);
;       } else {
;         const float* gn = (s < 14) ? qnc : knc;
;         const float rs = rsqrtf(sum16(x[0] * x[0] + x[1] * x[1]) * (1.0f / 32.0f) + EPS);
;         x[0] *= rs * gn[2 * hl16]; x[1] *= rs * gn[2 * hl16 + 1]; rope2<2>(x, hl16, cs8 + t * 4);
;         if (s < 14) x *= LOG2E * 0.17677669529663687f;
;         *(unsigned*)pp = pk2(x[0], x[1]);
.LBB0_290:
	s_or_b64 exec, exec, s[18:19]
	v_mul_f32_e32 v22, v32, v45
	s_waitcnt lgkmcnt(0)
	v_mul_f32_e32 v23, 0x3fb8aa3b, v22
	v_fma_f32 v44, v22, s64, -v23
	v_rndne_f32_e32 v45, v23
	v_fmac_f32_e32 v44, 0x32a5705f, v22
	v_sub_f32_e32 v23, v23, v45
	v_add_f32_e32 v23, v23, v44
	v_exp_f32_e32 v23, v23
	v_cvt_i32_f32_e32 v44, v45
	v_cmp_ngt_f32_e32 vcc, s65, v22
	v_ldexp_f32 v23, v23, v44
	s_nop 0
	v_cndmask_b32_e32 v23, 0, v23, vcc
	v_cmp_nlt_f32_e32 vcc, s89, v22
	s_nop 1
	v_cndmask_b32_e32 v22, v177, v23, vcc
	v_mul_f32_e32 v22, 0x3e000000, v22
	v_pk_mul_f32 v[20:21], v[22:23], v[20:21] op_sel_hi:[0,1]
	v_cvt_pk_bf16_f32 v22, v20, v21
	v_add_co_u32_e32 v20, vcc, s77, v18
	s_nop 1
	v_addc_co_u32_e32 v21, vcc, 0, v19, vcc
	global_store_dword v[20:21], v22, off offset:3712
	s_waitcnt vmcnt(27)
	v_lshlrev_b32_e32 v20, 16, v43
	v_and_b32_e32 v21, 0xffff0000, v43
	v_pk_mul_f32 v[22:23], v[20:21], v[20:21]
	s_nop 0
	v_add_f32_e32 v22, v22, v23
	s_nop 1
	v_add_f32_dpp v22, v22, v22 row_ror:8 row_mask:0xf bank_mask:0xf
	s_nop 1
	v_add_f32_dpp v22, v22, v22 row_ror:4 row_mask:0xf bank_mask:0xf
	s_nop 1
	v_add_f32_dpp v22, v22, v22 quad_perm:[2,3,0,1] row_mask:0xf bank_mask:0xf
	s_nop 1
	v_add_f32_dpp v22, v22, v22 quad_perm:[1,0,3,2] row_mask:0xf bank_mask:0xf
	v_fmamk_f32 v22, v22, 0x3d000000, v170
	v_cmp_gt_f32_e32 vcc, s33, v22
	v_mul_f32_e32 v23, 0x4b800000, v22
	s_nop 0
	v_cndmask_b32_e32 v22, v22, v23, vcc
	v_rsq_f32_e32 v22, v22
	s_nop 0
	v_mul_f32_e32 v23, 0x45800000, v22
	v_cndmask_b32_e32 v22, v22, v23, vcc
	v_pk_mul_f32 v[22:23], v[6:7], v[22:23] op_sel_hi:[1,0]
	s_nop 0
	v_pk_mul_f32 v[22:23], v[22:23], v[20:21]
	ds_bpermute_b32 v20, v29, v22
	ds_bpermute_b32 v21, v29, v23
	s_and_saveexec_b64 s[2:3], s[6:7]
	s_xor_b64 s[18:19], exec, s[2:3]
	s_cbranch_execz .LBB0_294
	s_and_saveexec_b64 s[30:31], s[8:9]
	s_cbranch_execz .LBB0_293
	ds_read_b128 v[44:47], v54 offset:32
	s_waitcnt lgkmcnt(0)
	v_pk_mul_f32 v[48:49], v[22:23], v[44:45]
	v_mul_f32_e32 v22, v45, v20
	v_mov_b32_e32 v20, v23
	v_pk_mul_f32 v[20:21], v[20:21], v[46:47]
	s_nop 0
	v_mov_b32_e32 v49, v20
	v_mov_b32_e32 v23, v21
	v_pk_add_f32 v[22:23], v[48:49], v[22:23]

; DI unsigned pk2(float lo, float hi) { f32x2 x = {lo, hi}; return __builtin_bit_cast(unsigned, __builtin_convertvector(x, bf16x2_t)); }
; DI float sum16(float v) { v += __shfl_xor(v, 8); v += __shfl_xor(v, 4); v += __shfl_xor(v, 2); v += __shfl_xor(v, 1); return v; }
; DI void post_unit(const Params& p, int l, int unit, LAS unsigned char* lds) {
;     ...
;       } else {
;         const float* gn = (s < 14) ? qnc : knc;
;         const float rs = rsqrtf(sum16(x[0] * x[0] + x[1] * x[1]) * (1.0f / 32.0f) + EPS);
;         x[0] *= rs * gn[2 * hl16]; x[1] *= rs * gn[2 * hl16 + 1]; rope2<2>(x, hl16, cs8 + t * 4);
;         if (s < 14) x *= LOG2E * 0.17677669529663687f;
;         *(unsigned*)pp = pk2(x[0], x[1]);
.LBB0_296:
	s_or_b64 exec, exec, s[18:19]
	s_mov_b32 s2, 0x3e8293ee
	s_waitcnt lgkmcnt(0)
	v_pk_mul_f32 v[20:21], v[22:23], s[2:3] op_sel_hi:[1,0]
	s_nop 0
	v_cvt_pk_bf16_f32 v22, v20, v21
	v_add_co_u32_e32 v20, vcc, 0xa003000, v18
	s_nop 1
	v_addc_co_u32_e32 v21, vcc, 0, v19, vcc
	global_store_dword v[20:21], v22, off offset:896
	s_waitcnt vmcnt(27)
	v_lshlrev_b32_e32 v20, 16, v42
	v_and_b32_e32 v21, 0xffff0000, v42
	v_pk_mul_f32 v[22:23], v[20:21], v[20:21]
	s_nop 0
	v_add_f32_e32 v22, v22, v23
	s_nop 1
	v_add_f32_dpp v22, v22, v22 row_ror:8 row_mask:0xf bank_mask:0xf
	s_nop 1
	v_add_f32_dpp v22, v22, v22 row_ror:4 row_mask:0xf bank_mask:0xf
	s_nop 1
	v_add_f32_dpp v22, v22, v22 quad_perm:[2,3,0,1] row_mask:0xf bank_mask:0xf
	s_nop 1
	v_add_f32_dpp v22, v22, v22 quad_perm:[1,0,3,2] row_mask:0xf bank_mask:0xf
	v_fmamk_f32 v22, v22, 0x3d000000, v170
	v_cmp_gt_f32_e32 vcc, s33, v22
	v_mul_f32_e32 v23, 0x4b800000, v22
	s_nop 0
	v_cndmask_b32_e32 v22, v22, v23, vcc
	v_rsq_f32_e32 v22, v22
	s_nop 0
	v_mul_f32_e32 v23, 0x45800000, v22
	v_cndmask_b32_e32 v22, v22, v23, vcc
	v_pk_mul_f32 v[22:23], v[6:7], v[22:23] op_sel_hi:[1,0]
	s_nop 0
	v_pk_mul_f32 v[22:23], v[22:23], v[20:21]
	ds_bpermute_b32 v20, v29, v22
	ds_bpermute_b32 v21, v29, v23
	s_and_saveexec_b64 s[2:3], s[6:7]
	s_xor_b64 s[18:19], exec, s[2:3]
	s_cbranch_execz .LBB0_300
	s_and_saveexec_b64 s[30:31], s[8:9]
	s_cbranch_execz .LBB0_299
	ds_read_b128 v[42:45], v54 offset:32
	s_waitcnt lgkmcnt(0)
	v_pk_mul_f32 v[46:47], v[22:23], v[42:43]
	v_mul_f32_e32 v22, v43, v20
	v_mov_b32_e32 v20, v23
	v_pk_mul_f32 v[20:21], v[20:21], v[44:45]
	s_nop 0
	v_mov_b32_e32 v47, v20
	v_mov_b32_e32 v23, v21
	v_pk_add_f32 v[22:23], v[46:47], v[22:23]

; DI unsigned pk2(float lo, float hi) { f32x2 x = {lo, hi}; return __builtin_bit_cast(unsigned, __builtin_convertvector(x, bf16x2_t)); }
; DI float sum16(float v) { v += __shfl_xor(v, 8); v += __shfl_xor(v, 4); v += __shfl_xor(v, 2); v += __shfl_xor(v, 1); return v; }
; DI void post_unit(const Params& p, int l, int unit, LAS unsigned char* lds) {
;     ...
;       } else {
;         const float* gn = (s < 14) ? qnc : knc;
;         const float rs = rsqrtf(sum16(x[0] * x[0] + x[1] * x[1]) * (1.0f / 32.0f) + EPS);
;         x[0] *= rs * gn[2 * hl16]; x[1] *= rs * gn[2 * hl16 + 1]; rope2<2>(x, hl16, cs8 + t * 4);
;         if (s < 14) x *= LOG2E * 0.17677669529663687f;
;         *(unsigned*)pp = pk2(x[0], x[1]);
.LBB0_302:
	s_or_b64 exec, exec, s[18:19]
	s_mov_b32 s2, 0x3e8293ee
	s_waitcnt lgkmcnt(0)
	v_pk_mul_f32 v[20:21], v[22:23], s[2:3] op_sel_hi:[1,0]
	s_nop 0
	v_cvt_pk_bf16_f32 v22, v20, v21
	v_add_co_u32_e32 v20, vcc, 0xa003000, v18
	s_nop 1
	v_addc_co_u32_e32 v21, vcc, 0, v19, vcc
	global_store_dword v[20:21], v22, off offset:1152
	s_waitcnt vmcnt(27)
	v_lshlrev_b32_e32 v20, 16, v41
	v_and_b32_e32 v21, 0xffff0000, v41
	v_pk_mul_f32 v[22:23], v[20:21], v[20:21]
	s_nop 0
	v_add_f32_e32 v22, v22, v23
	s_nop 1
	v_add_f32_dpp v22, v22, v22 row_ror:8 row_mask:0xf bank_mask:0xf
	s_nop 1
	v_add_f32_dpp v22, v22, v22 row_ror:4 row_mask:0xf bank_mask:0xf
	s_nop 1
	v_add_f32_dpp v22, v22, v22 quad_perm:[2,3,0,1] row_mask:0xf bank_mask:0xf
	s_nop 1
	v_add_f32_dpp v22, v22, v22 quad_perm:[1,0,3,2] row_mask:0xf bank_mask:0xf
	v_fmamk_f32 v22, v22, 0x3d000000, v170
	v_cmp_gt_f32_e32 vcc, s33, v22
	v_mul_f32_e32 v23, 0x4b800000, v22
	s_nop 0
	v_cndmask_b32_e32 v22, v22, v23, vcc
	v_rsq_f32_e32 v22, v22
	s_nop 0
	v_mul_f32_e32 v23, 0x45800000, v22
	v_cndmask_b32_e32 v22, v22, v23, vcc
	v_pk_mul_f32 v[22:23], v[8:9], v[22:23] op_sel_hi:[1,0]
	s_nop 0
	v_pk_mul_f32 v[22:23], v[22:23], v[20:21]
	ds_bpermute_b32 v20, v29, v22
	ds_bpermute_b32 v21, v29, v23
	s_and_saveexec_b64 s[2:3], s[6:7]
	s_xor_b64 s[18:19], exec, s[2:3]
	s_cbranch_execz .LBB0_306
	s_and_saveexec_b64 s[30:31], s[8:9]
	s_cbranch_execz .LBB0_305
	ds_read_b128 v[42:45], v54 offset:32
	s_waitcnt lgkmcnt(0)
	v_pk_mul_f32 v[46:47], v[22:23], v[42:43]
	v_mul_f32_e32 v22, v43, v20
	v_mov_b32_e32 v20, v23
	v_pk_mul_f32 v[20:21], v[20:21], v[44:45]
	s_nop 0
	v_mov_b32_e32 v47, v20
	v_mov_b32_e32 v23, v21
	v_pk_add_f32 v[22:23], v[46:47], v[22:23]

; DI unsigned pk2(float lo, float hi) { f32x2 x = {lo, hi}; return __builtin_bit_cast(unsigned, __builtin_convertvector(x, bf16x2_t)); }
; DI float sum16(float v) { v += __shfl_xor(v, 8); v += __shfl_xor(v, 4); v += __shfl_xor(v, 2); v += __shfl_xor(v, 1); return v; }
; DI void post_unit(const Params& p, int l, int unit, LAS unsigned char* lds) {
;     ...
;       } else {
;         const float* gn = (s < 14) ? qnc : knc;
;         const float rs = rsqrtf(sum16(x[0] * x[0] + x[1] * x[1]) * (1.0f / 32.0f) + EPS);
;         x[0] *= rs * gn[2 * hl16]; x[1] *= rs * gn[2 * hl16 + 1]; rope2<2>(x, hl16, cs8 + t * 4);
;         if (s < 14) x *= LOG2E * 0.17677669529663687f;
;         *(unsigned*)pp = pk2(x[0], x[1]);
.LBB0_308:
	s_or_b64 exec, exec, s[18:19]
	s_waitcnt lgkmcnt(1)
	v_add_co_u32_e32 v20, vcc, 0xa003000, v18
	v_cvt_pk_bf16_f32 v22, v22, v23
	s_waitcnt lgkmcnt(0)
	v_addc_co_u32_e32 v21, vcc, 0, v19, vcc
	global_store_dword v[20:21], v22, off offset:1408
	s_waitcnt vmcnt(27)
	v_lshlrev_b32_e32 v20, 16, v3
	v_and_b32_e32 v21, 0xffff0000, v3
	v_pk_mul_f32 v[22:23], v[20:21], v[20:21]
	s_nop 0
	v_add_f32_e32 v3, v22, v23
	s_nop 1
	v_add_f32_dpp v3, v3, v3 row_ror:8 row_mask:0xf bank_mask:0xf
	s_nop 1
	v_add_f32_dpp v3, v3, v3 row_ror:4 row_mask:0xf bank_mask:0xf
	s_nop 1
	v_add_f32_dpp v3, v3, v3 quad_perm:[2,3,0,1] row_mask:0xf bank_mask:0xf
	s_nop 1
	v_add_f32_dpp v3, v3, v3 quad_perm:[1,0,3,2] row_mask:0xf bank_mask:0xf
	v_fmamk_f32 v3, v3, 0x3d000000, v170
	v_cmp_gt_f32_e32 vcc, s33, v3
	v_mul_f32_e32 v22, 0x4b800000, v3
	s_nop 0
	v_cndmask_b32_e32 v3, v3, v22, vcc
	v_rsq_f32_e32 v3, v3
	s_nop 0
	v_mul_f32_e32 v22, 0x45800000, v3
	v_cndmask_b32_e32 v22, v3, v22, vcc
	v_pk_mul_f32 v[22:23], v[8:9], v[22:23] op_sel_hi:[1,0]
	s_nop 0
	v_pk_mul_f32 v[22:23], v[22:23], v[20:21]
	ds_bpermute_b32 v3, v29, v22
	ds_bpermute_b32 v21, v29, v23
	s_and_saveexec_b64 s[2:3], s[6:7]
	s_xor_b64 s[18:19], exec, s[2:3]
	s_cbranch_execz .LBB0_312
	s_and_saveexec_b64 s[30:31], s[8:9]
	s_cbranch_execz .LBB0_311
	ds_read_b128 v[42:45], v54 offset:32
	v_mov_b32_e32 v20, v23
	s_waitcnt lgkmcnt(0)
	v_pk_mul_f32 v[46:47], v[22:23], v[42:43]
	v_pk_mul_f32 v[20:21], v[20:21], v[44:45]
	v_mul_f32_e32 v22, v43, v3
	v_mov_b32_e32 v47, v20
	v_mov_b32_e32 v23, v21
	v_pk_add_f32 v[22:23], v[46:47], v[22:23]

.LBB0_370:
	ds_read_b128 v[208:211], v151
	ds_read_b128 v[212:215], v151 offset:32
	ds_read_b128 v[216:219], v151 offset:4608
	ds_read_b128 v[220:223], v151 offset:4640
	ds_read_b128 v[224:227], v151 offset:9216
	ds_read_b128 v[228:231], v151 offset:9248
	ds_read_b128 v[232:235], v151 offset:13824
	ds_read_b128 v[236:239], v151 offset:13856
	s_lshl_b32 s2, s29, 7
	v_cndmask_b32_e64 v158, v155, v157, s[6:7]
	s_cmp_le_u32 s2, s22
	s_waitcnt lgkmcnt(4)
	v_mfma_f32_32x32x16_bf16 v[50:65], v[66:69], v[208:211], 0
	ds_read_b128 v[208:211], v151 offset:64
	s_cselect_b64 s[18:19], -1, 0
	v_mfma_f32_32x32x16_bf16 v[50:65], v[70:73], v[212:215], v[50:65]
	ds_read_b128 v[212:215], v151 offset:4672
	v_mfma_f32_32x32x16_bf16 v[34:49], v[66:69], v[216:219], 0
	ds_read_b128 v[216:219], v151 offset:9280
	v_mfma_f32_32x32x16_bf16 v[34:49], v[70:73], v[220:223], v[34:49]
	ds_read_b128 v[220:223], v151 offset:13888
	s_waitcnt lgkmcnt(4)
	v_mfma_f32_32x32x16_bf16 v[18:33], v[66:69], v[224:227], 0
	ds_read_b128 v[224:227], v151 offset:96
	v_mfma_f32_32x32x16_bf16 v[18:33], v[70:73], v[228:231], v[18:33]
	ds_read_b128 v[228:231], v151 offset:4704
	v_mfma_f32_32x32x16_bf16 v[2:17], v[66:69], v[232:235], 0
	ds_read_b128 v[232:235], v151 offset:9312
	v_mfma_f32_32x32x16_bf16 v[2:17], v[70:73], v[236:239], v[2:17]
	ds_read_b128 v[236:239], v151 offset:13920
	s_waitcnt lgkmcnt(4)
	v_mfma_f32_32x32x16_bf16 v[50:65], v[74:77], v[208:211], v[50:65]
	v_mfma_f32_32x32x16_bf16 v[34:49], v[74:77], v[212:215], v[34:49]
	v_mfma_f32_32x32x16_bf16 v[18:33], v[74:77], v[216:219], v[18:33]
	v_mfma_f32_32x32x16_bf16 v[2:17], v[74:77], v[220:223], v[2:17]
	s_waitcnt lgkmcnt(0)
	v_mfma_f32_32x32x16_bf16 v[50:65], v[78:81], v[224:227], v[50:65]
	v_mfma_f32_32x32x16_bf16 v[34:49], v[78:81], v[228:231], v[34:49]
	s_nop 8
	v_fma_f32 v159, v107, v50, 0
	v_fma_f32 v50, v107, |v50|, v159
	v_fmac_f32_e32 v50, v108, v51
	v_fma_f32 v50, v108, |v51|, v50
	v_fmac_f32_e32 v50, v115, v52
	v_fma_f32 v50, v115, |v52|, v50
	v_fmac_f32_e32 v50, v116, v53
	v_fma_f32 v50, v116, |v53|, v50
	v_fmac_f32_e32 v50, v119, v54
	v_fma_f32 v50, v119, |v54|, v50
	v_mfma_f32_32x32x16_bf16 v[18:33], v[78:81], v[232:235], v[18:33]
	v_fmac_f32_e32 v50, v120, v55
	v_fma_f32 v50, v120, |v55|, v50
	v_fmac_f32_e32 v50, v125, v56
	v_fma_f32 v50, v125, |v56|, v50
	v_fmac_f32_e32 v50, v126, v57
	v_fma_f32 v50, v126, |v57|, v50
	v_mfma_f32_32x32x16_bf16 v[2:17], v[78:81], v[236:239], v[2:17]
	v_ashrrev_i32_e32 v52, 31, v50
	v_or_b32_e32 v51, s2, v128
	v_bitop3_b32 v50, v52, v50, s92 bitop3:0x36
	v_and_or_b32 v50, v50, s5, v51
	v_cmp_gt_u32_e32 vcc, v50, v158
	s_and_b64 vcc, vcc, s[18:19]
	s_cbranch_vccz .LBB0_376
	s_bcnt1_i32_b32 s3, vcc_lo
	v_mbcnt_lo_u32_b32 v53, vcc_lo, 0
	s_sub_i32 s12, s26, s3
	v_mbcnt_hi_u32_b32 v53, vcc_hi, v53
	s_addk_i32 s12, 0x600
	v_sub_u32_e32 v54, s12, v144
	s_bcnt1_i32_b32 s13, vcc_hi
	v_and_b32_e32 v54, v54, v148
	v_add3_u32 v53, v53, v144, v54
	v_lshl_add_u32 v53, v53, 2, v129
	s_mov_b64 exec, vcc
	ds_write_b32 v53, v50
	s_mov_b64 exec, -1
	v_add_u32_e32 v144, s3, v144
	s_add_i32 s26, s13, s26

.LBB0_551:
	ds_read_b128 v[208:211], v153
	ds_read_b128 v[212:215], v153 offset:32
	ds_read_b128 v[216:219], v153 offset:4608
	ds_read_b128 v[220:223], v153 offset:4640
	ds_read_b128 v[224:227], v153 offset:9216
	ds_read_b128 v[228:231], v153 offset:9248
	ds_read_b128 v[232:235], v153 offset:13824
	ds_read_b128 v[236:239], v153 offset:13856
	s_lshl_b32 s2, s2, 7
	v_cndmask_b32_e64 v158, v155, v157, s[6:7]
	s_cmp_le_u32 s2, s22
	s_waitcnt lgkmcnt(4)
	v_mfma_f32_32x32x16_bf16 v[50:65], v[66:69], v[208:211], 0
	ds_read_b128 v[208:211], v153 offset:64
	s_cselect_b64 s[18:19], -1, 0
	v_mfma_f32_32x32x16_bf16 v[50:65], v[70:73], v[212:215], v[50:65]
	ds_read_b128 v[212:215], v153 offset:4672
	v_mfma_f32_32x32x16_bf16 v[34:49], v[66:69], v[216:219], 0
	ds_read_b128 v[216:219], v153 offset:9280
	v_mfma_f32_32x32x16_bf16 v[34:49], v[70:73], v[220:223], v[34:49]
	ds_read_b128 v[220:223], v153 offset:13888
	s_waitcnt lgkmcnt(4)
	v_mfma_f32_32x32x16_bf16 v[18:33], v[66:69], v[224:227], 0
	ds_read_b128 v[224:227], v153 offset:96
	v_mfma_f32_32x32x16_bf16 v[18:33], v[70:73], v[228:231], v[18:33]
	ds_read_b128 v[228:231], v153 offset:4704
	v_mfma_f32_32x32x16_bf16 v[2:17], v[66:69], v[232:235], 0
	ds_read_b128 v[232:235], v153 offset:9312
	v_mfma_f32_32x32x16_bf16 v[2:17], v[70:73], v[236:239], v[2:17]
	ds_read_b128 v[236:239], v153 offset:13920
	s_waitcnt lgkmcnt(4)
	v_mfma_f32_32x32x16_bf16 v[50:65], v[74:77], v[208:211], v[50:65]
	v_mfma_f32_32x32x16_bf16 v[34:49], v[74:77], v[212:215], v[34:49]
	v_mfma_f32_32x32x16_bf16 v[18:33], v[74:77], v[216:219], v[18:33]
	v_mfma_f32_32x32x16_bf16 v[2:17], v[74:77], v[220:223], v[2:17]
	s_waitcnt lgkmcnt(0)
	v_mfma_f32_32x32x16_bf16 v[50:65], v[78:81], v[224:227], v[50:65]
	v_mfma_f32_32x32x16_bf16 v[34:49], v[78:81], v[228:231], v[34:49]
	s_nop 8
	v_fma_f32 v159, v107, v50, 0
	v_fma_f32 v50, v107, |v50|, v159
	v_fmac_f32_e32 v50, v108, v51
	v_fma_f32 v50, v108, |v51|, v50
	v_fmac_f32_e32 v50, v115, v52
	v_fma_f32 v50, v115, |v52|, v50
	v_fmac_f32_e32 v50, v116, v53
	v_fma_f32 v50, v116, |v53|, v50
	v_fmac_f32_e32 v50, v119, v54
	v_fma_f32 v50, v119, |v54|, v50
	v_mfma_f32_32x32x16_bf16 v[18:33], v[78:81], v[232:235], v[18:33]
	v_fmac_f32_e32 v50, v120, v55
	v_fma_f32 v50, v120, |v55|, v50
	v_fmac_f32_e32 v50, v125, v56
	v_fma_f32 v50, v125, |v56|, v50
	v_fmac_f32_e32 v50, v126, v57
	v_fma_f32 v50, v126, |v57|, v50
	v_mfma_f32_32x32x16_bf16 v[2:17], v[78:81], v[236:239], v[2:17]
	v_ashrrev_i32_e32 v52, 31, v50
	v_or_b32_e32 v51, s2, v128
	v_bitop3_b32 v50, v52, v50, s92 bitop3:0x36
	v_and_or_b32 v50, v50, s5, v51
	v_cmp_gt_u32_e32 vcc, v50, v158
	s_and_b64 vcc, vcc, s[18:19]
	s_cbranch_vccz .LBB0_557
	s_bcnt1_i32_b32 s3, vcc_lo
	v_mbcnt_lo_u32_b32 v53, vcc_lo, 0
	s_sub_i32 s12, s26, s3
	v_mbcnt_hi_u32_b32 v53, vcc_hi, v53
	s_addk_i32 s12, 0x600
	v_sub_u32_e32 v54, s12, v144
	s_bcnt1_i32_b32 s13, vcc_hi
	v_and_b32_e32 v54, v54, v148
	v_add3_u32 v53, v53, v144, v54
	v_lshl_add_u32 v53, v53, 2, v129
	s_mov_b64 exec, vcc
	ds_write_b32 v53, v50
	s_mov_b64 exec, -1
	v_add_u32_e32 v144, s3, v144
	s_add_i32 s26, s13, s26

; #define LAS __attribute__((address_space(3)))
; DI void dsa_unit(const Params& p, int l, int b, int g32, LAS unsigned char* lds) {
;     ...
;   LAS unsigned char* vt = lds + A_KT + w * VT_BYTES;
;   const u16* kvc = (const u16*)(p.ws + WS_KVC);
;   const int ks = lane >> 3, dg = lane & 7;
.LBB0_896:
	s_movk_i32 s2, 0x1200
	v_mul_lo_u32 v2, v104, s2
	v_add_u32_e32 v8, s24, v2
	v_lshlrev_b32_e32 v2, 7, v128
	v_mov_b32_e32 v3, v1
	v_lshl_add_u64 v[4:5], s[56:57], 0, v[2:3]
	v_lshlrev_b32_e32 v6, 1, v106
	v_mov_b32_e32 v7, v1
	v_add_u32_e32 v3, v8, v0
	v_bfe_u32 v0, v103, 2, 2
	v_lshl_add_u64 v[114:115], v[4:5], 0, v[6:7]
	v_readlane_b32 s2, v252, 53
	v_and_b32_e32 v4, 16, v103
	v_lshl_or_b32 v0, v102, 2, v0
	v_lshlrev_b32_e32 v5, 2, v123
	v_readlane_b32 s3, v252, 54
	v_and_or_b32 v4, v5, 12, v4
	v_mad_u32_u24 v5, v0, s59, v8
	v_lshlrev_b32_e32 v0, 1, v105
	v_lshl_add_u64 v[116:117], s[2:3], 0, v[6:7]
	v_lshl_add_u64 v[118:119], s[2:3], 0, v[0:1]
	v_readlane_b32 s2, v251, 27
	v_lshrrev_b32_e32 v146, 3, v123
	v_lshl_or_b32 v0, v102, 3, v2
	v_readlane_b32 s3, v251, 28
	v_lshl_add_u64 v[120:121], s[56:57], 0, v[0:1]
	v_lshlrev_b32_e32 v4, 1, v4
	v_lshl_add_u64 v[124:125], s[2:3], 0, v[0:1]
	v_lshlrev_b32_e32 v0, 2, v146
	s_add_i32 s2, 0, 0x80
	v_mul_u32_u24_e32 v6, 0x90, v146
	v_add3_u32 v149, v99, v0, s2
	v_lshlrev_b32_e32 v0, 2, v128
	v_cmp_gt_u32_e64 s[6:7], 4, v128
	v_or_b32_e32 v147, 0x100, v123
	v_or_b32_e32 v148, 0x140, v123
	v_add3_u32 v150, v99, v0, s2
	s_mov_b32 s28, 0
	v_add_u32_e32 v151, v3, v6
	v_add_u32_e32 v152, v5, v4
	v_lshlrev_b32_e32 v216, 1, v106
	v_lshlrev_b32_e32 v217, 1, v105
	s_branch .LBB0_898

; DI f32x16 zero16() { f32x16 z; for (int i = 0; i < 16; ++i) z[i] = 0.f; return z; }
; DI void dsa_unit(const Params& p, int l, int b, int g32, LAS unsigned char* lds) {
;     ...
;     bf16x8 qb[4];
; #pragma unroll
;     for (int s = 0; s < 4; ++s) { u32x4 z = {0u, 0u, 0u, 0u}; if (r < 4) z = *(const u32x4*)(proj + tq * NP + C_QA + r * 64 + 16 * s + 8 * h); qb[s] = __builtin_bit_cast(bf16x8, z); }
;     f32x16 o[2] = {zero16(), zero16()}; float lsum = 0.f;
;     u32x4 ka[4], va4[4];
;     {
;       const unsigned ik = cq[r] & 0x1FFFu; const u16* kp = kvc + ((size_t)b * S + ik) * 128 + 8 * h;
; #pragma unroll
;       for (int s = 0; s < 4; ++s) ka[s] = *(const u32x4*)(kp + 16 * s);
; #pragma unroll
;       for (int u = 0; u < 4; ++u) { const unsigned iv = cq[8 * u + ks] & 0x1FFFu; va4[u] = *(const u32x4*)(kvc + ((size_t)b * S + iv) * 128 + 64 + 8 * dg); }
;     }
.LBB0_955:
	s_or_b64 exec, exec, s[8:9]
	v_ashrrev_i32_e32 v127, 5, v13
	v_mov_b32_e32 v17, 0
	v_cmp_lt_i32_e32 vcc, 0, v127
	v_mov_b32_e32 v16, 0
	v_mov_b32_e32 v15, 0
	v_mov_b32_e32 v14, 0
	v_mov_b32_e32 v13, 0
	v_mov_b32_e32 v12, 0
	v_mov_b32_e32 v11, 0
	v_mov_b32_e32 v10, 0
	v_mov_b32_e32 v9, 0
	v_mov_b32_e32 v8, 0
	v_mov_b32_e32 v7, 0
	v_mov_b32_e32 v6, 0
	v_mov_b32_e32 v5, 0
	v_mov_b32_e32 v4, 0
	v_mov_b32_e32 v3, 0
	v_mov_b32_e32 v2, 0
	v_mov_b32_e32 v33, 0
	v_mov_b32_e32 v32, 0
	v_mov_b32_e32 v31, 0
	v_mov_b32_e32 v30, 0
	v_mov_b32_e32 v29, 0
	v_mov_b32_e32 v28, 0
	v_mov_b32_e32 v27, 0
	v_mov_b32_e32 v26, 0
	v_mov_b32_e32 v25, 0
	v_mov_b32_e32 v24, 0
	v_mov_b32_e32 v23, 0
	v_mov_b32_e32 v22, 0
	v_mov_b32_e32 v21, 0
	v_mov_b32_e32 v20, 0
	v_mov_b32_e32 v19, 0
	v_mov_b32_e32 v18, 0
	v_mov_b32_e32 v153, 0
	s_and_saveexec_b64 s[8:9], vcc
	s_cbranch_execz .LBB0_961
	v_readlane_b32 s100, v252, 53
	v_readlane_b32 s101, v252, 54
	s_lshl_b32 s12, s0, 8
	s_add_u32 s100, s100, s12
	s_addc_u32 s101, s101, 0
	s_nop 0
	v_readfirstlane_b32 s2, v127
	s_mov_b64 s[10:11], 0
	v_lshl_add_u32 v154, v128, 2, v34
	v_lshl_add_u32 v155, v146, 2, v34
	ds_read_b32 v174, v154
	ds_read2_b32 v[176:177], v155 offset0:0 offset1:8
	ds_read2_b32 v[178:179], v155 offset0:16 offset1:24
	s_waitcnt lgkmcnt(0)
	v_bfe_u32 v0, v174, 0, 13
	v_lshl_add_u32 v182, v0, 8, v216
	global_load_dwordx4 v[170:173], v182, s[100:101]
	global_load_dwordx4 v[106:109], v182, s[100:101] offset:32
	global_load_dwordx4 v[102:105], v182, s[100:101] offset:64
	global_load_dwordx4 v[98:101], v182, s[100:101] offset:96
	v_bfe_u32 v0, v176, 0, 13
	v_lshl_add_u32 v182, v0, 8, v217
	global_load_dwordx4 v[78:81], v182, s[100:101] offset:128
	v_bfe_u32 v0, v177, 0, 13
	v_lshl_add_u32 v182, v0, 8, v217
	global_load_dwordx4 v[74:77], v182, s[100:101] offset:128
	v_bfe_u32 v0, v178, 0, 13
	v_lshl_add_u32 v182, v0, 8, v217
	global_load_dwordx4 v[70:73], v182, s[100:101] offset:128
	v_bfe_u32 v0, v179, 0, 13
	v_lshl_add_u32 v182, v0, 8, v217
	global_load_dwordx4 v[66:69], v182, s[100:101] offset:128
	ds_read_b32 v174, v154 offset:128
	ds_read2_b32 v[176:177], v155 offset0:32 offset1:40
	ds_read2_b32 v[178:179], v155 offset0:48 offset1:56
	s_waitcnt lgkmcnt(0)
	v_bfe_u32 v0, v174, 0, 13
	v_lshl_add_u32 v182, v0, 8, v216
	global_load_dwordx4 v[94:97], v182, s[100:101]
	global_load_dwordx4 v[90:93], v182, s[100:101] offset:32
	global_load_dwordx4 v[86:89], v182, s[100:101] offset:64
	global_load_dwordx4 v[82:85], v182, s[100:101] offset:96
	v_bfe_u32 v0, v176, 0, 13
	v_lshl_add_u32 v182, v0, 8, v217
	global_load_dwordx4 v[156:159], v182, s[100:101] offset:128
	v_bfe_u32 v0, v177, 0, 13
	v_lshl_add_u32 v182, v0, 8, v217
	global_load_dwordx4 v[160:163], v182, s[100:101] offset:128
	v_bfe_u32 v0, v178, 0, 13
	v_lshl_add_u32 v182, v0, 8, v217
	global_load_dwordx4 v[130:133], v182, s[100:101] offset:128
	v_bfe_u32 v0, v179, 0, 13
	v_lshl_add_u32 v182, v0, 8, v217
	global_load_dwordx4 v[134:137], v182, s[100:101] offset:128
	v_add_u32_e32 v154, 0x100, v154
	v_add_u32_e32 v155, 0x100, v155
	s_mov_b32 s3, 0
; #define LAS __attribute__((address_space(3)))
; #define MFMA32(a, b, c) __builtin_amdgcn_mfma_f32_32x32x16_bf16((a), (b), (c), 0, 0, 0)
; DI float fexp2(float x) { return __builtin_amdgcn_exp2f(x); }
; DI f32x16 zero16() { f32x16 z; for (int i = 0; i < 16; ++i) z[i] = 0.f; return z; }
; DI void lds_wave_sync() { asm volatile("s_waitcnt lgkmcnt(0)" ::: "memory"); __builtin_amdgcn_wave_barrier(); asm volatile("" ::: "memory"); }
; DI void dsa_unit(const Params& p, int l, int b, int g32, LAS unsigned char* lds) {
;     ...
;     for (int mt = 0; mt < ntile; ++mt) {
;       bf16x8 a[4];
; #pragma unroll
;       for (int s = 0; s < 4; ++s) a[s] = __builtin_bit_cast(bf16x8, ka[s]);
; #pragma unroll
;       for (int u = 0; u < 4; ++u) *(LAS u32x4*)(vt + (8 * u + ks) * KT_RS + dg * 16) = va4[u];
;       if (mt + 1 < ntile) {
;         const unsigned ik = cq[32 * (mt + 1) + r] & 0x1FFFu; const u16* kp = kvc + ((size_t)b * S + ik) * 128 + 8 * h;
; #pragma unroll
;         for (int s = 0; s < 4; ++s) ka[s] = *(const u32x4*)(kp + 16 * s);
; #pragma unroll
;         for (int u = 0; u < 4; ++u) { const unsigned iv = cq[32 * (mt + 1) + 8 * u + ks] & 0x1FFFu; va4[u] = *(const u32x4*)(kvc + ((size_t)b * S + iv) * 128 + 64 + 8 * dg); }
;       }
;       f32x16 sc = zero16();
; #pragma unroll
;       for (int s = 0; s < 4; ++s) sc = MFMA32(a[s], qb[s], sc);
; #pragma unroll
;       for (int i = 0; i < 16; ++i) { sc[i] = fexp2(sc[i]); lsum += sc[i]; }
;       lds_wave_sync();
; #pragma unroll
;       for (int s = 0; s < 2; ++s) {
;         const bf16x8 pf = pack8(sc, s);
; #pragma unroll
;         for (int et = 0; et < 2; ++et) { const bf16x8 vf = vfrag144(vt, 16 * s + 4 * h, 32 * et, lane); o[et] = MFMA32(vf, pf, o[et]); }
;       }
;       lds_wave_sync();
;     }
.Lmy_g_loop:
	s_add_i32 s12, s3, 2
	s_cmp_lt_u32 s12, s2
	s_cbranch_scc0 .Lmy_g_last
	s_waitcnt vmcnt(8)
	ds_write_b128 v151, v[78:81]
	ds_write_b128 v151, v[74:77] offset:1152
	ds_write_b128 v151, v[70:73] offset:2304
	ds_write_b128 v151, v[66:69] offset:3456
	v_mfma_f32_32x32x16_bf16 v[34:49], v[170:173], v[54:57], 0
	s_waitcnt lgkmcnt(0)
	v_mfma_f32_32x32x16_bf16 v[34:49], v[106:109], v[50:53], v[34:49]
	v_mfma_f32_32x32x16_bf16 v[34:49], v[102:105], v[62:65], v[34:49]
	v_mfma_f32_32x32x16_bf16 v[34:49], v[98:101], v[58:61], v[34:49]
	ds_read_b64_tr_b16 v[184:185], v152 offset:64
	ds_read_b64_tr_b16 v[186:187], v152 offset:1216
	ds_read_b32 v174, v154
	ds_read2_b32 v[176:177], v155 offset0:0 offset1:8
	ds_read2_b32 v[178:179], v155 offset0:16 offset1:24
	s_waitcnt lgkmcnt(0)
	v_bfe_u32 v0, v174, 0, 13
	v_lshl_add_u32 v182, v0, 8, v216
	global_load_dwordx4 v[170:173], v182, s[100:101]
	global_load_dwordx4 v[106:109], v182, s[100:101] offset:32
	global_load_dwordx4 v[102:105], v182, s[100:101] offset:64
	global_load_dwordx4 v[98:101], v182, s[100:101] offset:96
	v_bfe_u32 v0, v176, 0, 13
	v_lshl_add_u32 v182, v0, 8, v217
	global_load_dwordx4 v[78:81], v182, s[100:101] offset:128
	v_bfe_u32 v0, v177, 0, 13
	v_lshl_add_u32 v182, v0, 8, v217
	global_load_dwordx4 v[74:77], v182, s[100:101] offset:128
	v_bfe_u32 v0, v178, 0, 13
	v_lshl_add_u32 v182, v0, 8, v217
	global_load_dwordx4 v[70:73], v182, s[100:101] offset:128
	v_bfe_u32 v0, v179, 0, 13
	v_lshl_add_u32 v182, v0, 8, v217
	global_load_dwordx4 v[66:69], v182, s[100:101] offset:128
	v_exp_f32_e32 v34, v34
	v_exp_f32_e32 v35, v35
	v_exp_f32_e32 v36, v36
	v_exp_f32_e32 v37, v37
	v_exp_f32_e32 v38, v38
	v_exp_f32_e32 v39, v39
	v_exp_f32_e32 v40, v40
	v_exp_f32_e32 v41, v41
	v_add_f32_e32 v153, v153, v34
	v_add_f32_e32 v153, v153, v35
	v_add_f32_e32 v153, v153, v36
	v_add_f32_e32 v153, v153, v37
	v_add_f32_e32 v153, v153, v38
	v_add_f32_e32 v153, v153, v39
	v_add_f32_e32 v153, v153, v40
	v_add_f32_e32 v153, v153, v41
	v_cvt_pk_bf16_f32 v34, v34, v35
	v_cvt_pk_bf16_f32 v35, v36, v37
	v_cvt_pk_bf16_f32 v36, v38, v39
	v_cvt_pk_bf16_f32 v37, v40, v41
	ds_read_b64_tr_b16 v[38:39], v152
	ds_read_b64_tr_b16 v[40:41], v152 offset:1152
	v_exp_f32_e32 v42, v42
	v_exp_f32_e32 v43, v43
	v_exp_f32_e32 v44, v44
	v_exp_f32_e32 v45, v45
	v_exp_f32_e32 v46, v46
	v_exp_f32_e32 v47, v47
	v_exp_f32_e32 v48, v48
	v_exp_f32_e32 v49, v49
	s_waitcnt lgkmcnt(0)
	v_mfma_f32_32x32x16_bf16 v[18:33], v[38:41], v[34:37], v[18:33]
	ds_read_b64_tr_b16 v[38:39], v152 offset:2304
	ds_read_b64_tr_b16 v[40:41], v152 offset:3456
	v_mfma_f32_32x32x16_bf16 v[2:17], v[184:187], v[34:37], v[2:17]
	ds_read_b64_tr_b16 v[184:185], v152 offset:2368
	ds_read_b64_tr_b16 v[186:187], v152 offset:3520
	v_cvt_pk_bf16_f32 v34, v42, v43
	v_cvt_pk_bf16_f32 v35, v44, v45
	v_cvt_pk_bf16_f32 v36, v46, v47
	v_cvt_pk_bf16_f32 v37, v48, v49
	v_add_f32_e32 v153, v153, v42
	v_add_f32_e32 v153, v153, v43
	v_add_f32_e32 v153, v153, v44
	v_add_f32_e32 v153, v153, v45
	v_add_f32_e32 v153, v153, v46
	v_add_f32_e32 v153, v153, v47
	v_add_f32_e32 v153, v153, v48
	v_add_f32_e32 v153, v153, v49
	s_waitcnt lgkmcnt(2)
	v_mfma_f32_32x32x16_bf16 v[18:33], v[38:41], v[34:37], v[18:33]
	s_waitcnt lgkmcnt(0)
	v_mfma_f32_32x32x16_bf16 v[2:17], v[184:187], v[34:37], v[2:17]
	s_waitcnt vmcnt(8)
	ds_write_b128 v151, v[156:159]
	ds_write_b128 v151, v[160:163] offset:1152
	ds_write_b128 v151, v[130:133] offset:2304
	ds_write_b128 v151, v[134:137] offset:3456
	v_mfma_f32_32x32x16_bf16 v[34:49], v[94:97], v[54:57], 0
	s_waitcnt lgkmcnt(0)
	v_mfma_f32_32x32x16_bf16 v[34:49], v[90:93], v[50:53], v[34:49]
	v_mfma_f32_32x32x16_bf16 v[34:49], v[86:89], v[62:65], v[34:49]
	v_mfma_f32_32x32x16_bf16 v[34:49], v[82:85], v[58:61], v[34:49]
	ds_read_b64_tr_b16 v[184:185], v152 offset:64
	ds_read_b64_tr_b16 v[186:187], v152 offset:1216
	ds_read_b32 v174, v154 offset:128
	ds_read2_b32 v[176:177], v155 offset0:32 offset1:40
	ds_read2_b32 v[178:179], v155 offset0:48 offset1:56
	s_waitcnt lgkmcnt(0)
	v_bfe_u32 v0, v174, 0, 13
	v_lshl_add_u32 v182, v0, 8, v216
	global_load_dwordx4 v[94:97], v182, s[100:101]
	global_load_dwordx4 v[90:93], v182, s[100:101] offset:32
	global_load_dwordx4 v[86:89], v182, s[100:101] offset:64
	global_load_dwordx4 v[82:85], v182, s[100:101] offset:96
	v_bfe_u32 v0, v176, 0, 13
	v_lshl_add_u32 v182, v0, 8, v217
	global_load_dwordx4 v[156:159], v182, s[100:101] offset:128
	v_bfe_u32 v0, v177, 0, 13
	v_lshl_add_u32 v182, v0, 8, v217
	global_load_dwordx4 v[160:163], v182, s[100:101] offset:128
	v_bfe_u32 v0, v178, 0, 13
	v_lshl_add_u32 v182, v0, 8, v217
	global_load_dwordx4 v[130:133], v182, s[100:101] offset:128
	v_bfe_u32 v0, v179, 0, 13
	v_lshl_add_u32 v182, v0, 8, v217
	global_load_dwordx4 v[134:137], v182, s[100:101] offset:128
	v_exp_f32_e32 v34, v34
	v_exp_f32_e32 v35, v35
	v_exp_f32_e32 v36, v36
	v_exp_f32_e32 v37, v37
	v_exp_f32_e32 v38, v38
	v_exp_f32_e32 v39, v39
	v_exp_f32_e32 v40, v40
	v_exp_f32_e32 v41, v41
	v_add_f32_e32 v153, v153, v34
	v_add_f32_e32 v153, v153, v35
	v_add_f32_e32 v153, v153, v36
	v_add_f32_e32 v153, v153, v37
	v_add_f32_e32 v153, v153, v38
	v_add_f32_e32 v153, v153, v39
	v_add_f32_e32 v153, v153, v40
	v_add_f32_e32 v153, v153, v41
	v_cvt_pk_bf16_f32 v34, v34, v35
	v_cvt_pk_bf16_f32 v35, v36, v37
	v_cvt_pk_bf16_f32 v36, v38, v39
	v_cvt_pk_bf16_f32 v37, v40, v41
	ds_read_b64_tr_b16 v[38:39], v152
	ds_read_b64_tr_b16 v[40:41], v152 offset:1152
	v_exp_f32_e32 v42, v42
	v_exp_f32_e32 v43, v43
	v_exp_f32_e32 v44, v44
	v_exp_f32_e32 v45, v45
	v_exp_f32_e32 v46, v46
	v_exp_f32_e32 v47, v47
	v_exp_f32_e32 v48, v48
	v_exp_f32_e32 v49, v49
	s_waitcnt lgkmcnt(0)
	v_mfma_f32_32x32x16_bf16 v[18:33], v[38:41], v[34:37], v[18:33]
	ds_read_b64_tr_b16 v[38:39], v152 offset:2304
	ds_read_b64_tr_b16 v[40:41], v152 offset:3456
	v_mfma_f32_32x32x16_bf16 v[2:17], v[184:187], v[34:37], v[2:17]
	ds_read_b64_tr_b16 v[184:185], v152 offset:2368
	ds_read_b64_tr_b16 v[186:187], v152 offset:3520
	v_cvt_pk_bf16_f32 v34, v42, v43
	v_cvt_pk_bf16_f32 v35, v44, v45
	v_cvt_pk_bf16_f32 v36, v46, v47
	v_cvt_pk_bf16_f32 v37, v48, v49
	v_add_f32_e32 v153, v153, v42
	v_add_f32_e32 v153, v153, v43
	v_add_f32_e32 v153, v153, v44
	v_add_f32_e32 v153, v153, v45
	v_add_f32_e32 v153, v153, v46
	v_add_f32_e32 v153, v153, v47
	v_add_f32_e32 v153, v153, v48
	v_add_f32_e32 v153, v153, v49
	s_waitcnt lgkmcnt(2)
	v_mfma_f32_32x32x16_bf16 v[18:33], v[38:41], v[34:37], v[18:33]
	s_waitcnt lgkmcnt(0)
	v_mfma_f32_32x32x16_bf16 v[2:17], v[184:187], v[34:37], v[2:17]
	v_add_u32_e32 v154, 0x100, v154
	v_add_u32_e32 v155, 0x100, v155
	s_mov_b32 s3, s12
	s_branch .Lmy_g_loop
